# glu epilogue: Y/Z staging loads through a 14-slot register FIFO issued ahead of use
# baseline (speedup 1.0000x reference)
.LBB0_674:
	s_lshl_b32 s20, s95, 2
	s_mov_b32 s21, s7
	v_lshl_add_u64 v[174:175], v[132:133], 0, s[20:21]
	global_load_dword v145, v[174:175], off
	global_load_dword v144, v[174:175], off offset:64
	global_load_dword v143, v[174:175], off offset:128
	global_load_dword v142, v[174:175], off offset:192
	v_lshlrev_b64 v[140:141], 11, v[140:141]
	s_lshl_b32 s6, s6, 8
	v_lshl_add_u64 v[140:141], v[128:129], 0, v[140:141]
	v_lshl_add_u64 v[140:141], v[140:141], 0, s[6:7]
	v_lshl_add_u64 v[140:141], v[140:141], 1, v[136:137]
	s_mov_b64 s[64:65], 0
	v_mov_b32_e32 v174, v171
	s_mov_b64 s[64:65], 0xa000000
	v_lshl_add_u64 v[250:251], v[140:141], 0, s[64:65]
	s_mov_b64 s[64:65], 0x8000
	global_load_dwordx4 v[194:197], v[250:251], off
	v_lshl_add_u64 v[250:251], v[250:251], 0, s[64:65]
	global_load_dwordx4 v[198:201], v[250:251], off
	v_lshl_add_u64 v[250:251], v[250:251], 0, s[64:65]
	global_load_dwordx4 v[202:205], v[250:251], off
	v_lshl_add_u64 v[250:251], v[250:251], 0, s[64:65]
	global_load_dwordx4 v[206:209], v[250:251], off
	v_lshl_add_u64 v[250:251], v[250:251], 0, s[64:65]
	global_load_dwordx4 v[210:213], v[250:251], off
	v_lshl_add_u64 v[250:251], v[250:251], 0, s[64:65]
	global_load_dwordx4 v[214:217], v[250:251], off
	v_lshl_add_u64 v[250:251], v[250:251], 0, s[64:65]
	global_load_dwordx4 v[218:221], v[250:251], off
	v_lshl_add_u64 v[250:251], v[250:251], 0, s[64:65]
	global_load_dwordx4 v[222:225], v[250:251], off
	s_mov_b64 s[64:65], 0x6000000
	v_lshl_add_u64 v[250:251], v[140:141], 0, s[64:65]
	s_mov_b64 s[64:65], 0x8000
	global_load_dwordx4 v[226:229], v[250:251], off
	v_lshl_add_u64 v[250:251], v[250:251], 0, s[64:65]
	global_load_dwordx4 v[230:233], v[250:251], off
	v_lshl_add_u64 v[250:251], v[250:251], 0, s[64:65]
	global_load_dwordx4 v[234:237], v[250:251], off
	v_lshl_add_u64 v[250:251], v[250:251], 0, s[64:65]
	global_load_dwordx4 v[238:241], v[250:251], off
	v_lshl_add_u64 v[250:251], v[250:251], 0, s[64:65]
	global_load_dwordx4 v[242:245], v[250:251], off
	v_lshl_add_u64 v[250:251], v[250:251], 0, s[64:65]
	global_load_dwordx4 v[246:249], v[250:251], off
	v_lshl_add_u64 v[250:251], v[250:251], 0, s[64:65]
	s_waitcnt vmcnt(13)
	ds_write_b128 v171, v[194:197]
	s_waitcnt vmcnt(12)
	ds_write_b128 v171, v[198:201] offset:1152
	s_mov_b64 s[64:65], 0x8000
	global_load_dwordx4 v[194:197], v[250:251], off
	v_lshl_add_u64 v[250:251], v[250:251], 0, s[64:65]
	global_load_dwordx4 v[198:201], v[250:251], off
	s_waitcnt vmcnt(13)
	ds_write_b128 v171, v[202:205] offset:2304
	s_waitcnt vmcnt(12)
	ds_write_b128 v171, v[206:209] offset:3456
	s_waitcnt vmcnt(11)
	ds_write_b128 v171, v[210:213] offset:4608
	s_waitcnt vmcnt(10)
	ds_write_b128 v171, v[214:217] offset:5760
	s_waitcnt vmcnt(9)
	ds_write_b128 v171, v[218:221] offset:6912
	s_waitcnt vmcnt(8)
	ds_write_b128 v171, v[222:225] offset:8064
	s_waitcnt vmcnt(7)
	ds_write_b128 v130, v[226:229]
	s_waitcnt vmcnt(6)
	ds_write_b128 v130, v[230:233] offset:1152
	s_waitcnt vmcnt(5)
	ds_write_b128 v130, v[234:237] offset:2304
	s_waitcnt vmcnt(4)
	ds_write_b128 v130, v[238:241] offset:3456
	s_waitcnt vmcnt(3)
	ds_write_b128 v130, v[242:245] offset:4608
	s_waitcnt vmcnt(2)
	ds_write_b128 v130, v[246:249] offset:5760
	s_waitcnt vmcnt(1)
	ds_write_b128 v130, v[194:197] offset:6912
	s_waitcnt vmcnt(0)
	ds_write_b128 v130, v[198:201] offset:8064
	s_mov_b64 s[64:65], 0xa040000
	v_lshl_add_u64 v[250:251], v[138:139], 0, s[64:65]
	s_mov_b64 s[64:65], 0x8000
	global_load_dwordx4 v[194:197], v[250:251], off
	v_lshl_add_u64 v[250:251], v[250:251], 0, s[64:65]
	global_load_dwordx4 v[198:201], v[250:251], off
	v_lshl_add_u64 v[250:251], v[250:251], 0, s[64:65]
	global_load_dwordx4 v[202:205], v[250:251], off
	v_lshl_add_u64 v[250:251], v[250:251], 0, s[64:65]
	global_load_dwordx4 v[206:209], v[250:251], off
	v_lshl_add_u64 v[250:251], v[250:251], 0, s[64:65]
	global_load_dwordx4 v[210:213], v[250:251], off
	v_lshl_add_u64 v[250:251], v[250:251], 0, s[64:65]
	global_load_dwordx4 v[214:217], v[250:251], off
	v_lshl_add_u64 v[250:251], v[250:251], 0, s[64:65]
	global_load_dwordx4 v[218:221], v[250:251], off
	v_lshl_add_u64 v[250:251], v[250:251], 0, s[64:65]
	global_load_dwordx4 v[222:225], v[250:251], off
	s_mov_b64 s[64:65], 0x6040000
	v_lshl_add_u64 v[250:251], v[138:139], 0, s[64:65]
	s_mov_b64 s[64:65], 0x8000
	global_load_dwordx4 v[226:229], v[250:251], off
	v_lshl_add_u64 v[250:251], v[250:251], 0, s[64:65]
	global_load_dwordx4 v[230:233], v[250:251], off
	v_lshl_add_u64 v[250:251], v[250:251], 0, s[64:65]
	global_load_dwordx4 v[234:237], v[250:251], off
	v_lshl_add_u64 v[250:251], v[250:251], 0, s[64:65]
	global_load_dwordx4 v[238:241], v[250:251], off
	v_lshl_add_u64 v[250:251], v[250:251], 0, s[64:65]
	global_load_dwordx4 v[242:245], v[250:251], off
	v_lshl_add_u64 v[250:251], v[250:251], 0, s[64:65]
	global_load_dwordx4 v[246:249], v[250:251], off
	v_lshl_add_u64 v[250:251], v[250:251], 0, s[64:65]
	v_add_f32_e32 v124, v124, v145
	v_mul_f32_e32 v124, 0xbfb8aa3b, v124
	v_exp_f32_e32 v124, v124
	s_waitcnt lgkmcnt(0)
	ds_read_u16 v174, v148
	ds_read_u16 v175, v148 offset:9216
	v_add_f32_e32 v125, v125, v145
	v_add_f32_e32 v124, 1.0, v124
	v_rcp_f32_e32 v124, v124
	s_waitcnt lgkmcnt(1)
	v_lshlrev_b32_e32 v174, 16, v174
	s_waitcnt lgkmcnt(0)
	v_lshlrev_b32_e32 v175, 16, v175
	v_mul_f32_e32 v125, 0xbfb8aa3b, v125
	v_mul_f32_e32 v124, v124, v174
	v_mul_f32_e32 v124, v124, v175
	v_exp_f32_e32 v125, v125
	v_cvt_pk_bf16_f32 v124, v124, s0
	ds_write_b16 v148, v124 offset:9216
	ds_read_u16 v124, v147 offset:144
	v_add_f32_e32 v125, 1.0, v125
	ds_read_u16 v174, v147 offset:9360
	v_rcp_f32_e32 v125, v125
	v_add_f32_e32 v120, v120, v144
	s_waitcnt lgkmcnt(1)
	v_lshlrev_b32_e32 v124, 16, v124
	v_mul_f32_e32 v120, 0xbfb8aa3b, v120
	v_mul_f32_e32 v124, v125, v124
	s_waitcnt lgkmcnt(0)
	v_lshlrev_b32_e32 v125, 16, v174
	v_mul_f32_e32 v124, v124, v125
	v_add_f32_e32 v125, v126, v145
	v_mul_f32_e32 v125, 0xbfb8aa3b, v125
	v_exp_f32_e32 v125, v125
	v_cvt_pk_bf16_f32 v124, v124, s0
	ds_write_b16 v147, v124 offset:9360
	ds_read_u16 v124, v149
	v_add_f32_e32 v125, 1.0, v125
	ds_read_u16 v126, v149 offset:9216
	v_rcp_f32_e32 v125, v125
	v_exp_f32_e32 v120, v120
	s_waitcnt lgkmcnt(1)
	v_lshlrev_b32_e32 v124, 16, v124
	v_add_f32_e32 v121, v121, v144
	v_mul_f32_e32 v124, v125, v124
	s_waitcnt lgkmcnt(0)
	v_lshlrev_b32_e32 v125, 16, v126
	v_mul_f32_e32 v124, v124, v125
	v_add_f32_e32 v125, v127, v145
	v_mul_f32_e32 v125, 0xbfb8aa3b, v125
	v_exp_f32_e32 v125, v125
	v_cvt_pk_bf16_f32 v124, v124, s0
	ds_write_b16 v149, v124 offset:9216
	ds_read_u16 v124, v151
	v_add_f32_e32 v125, 1.0, v125
	v_rcp_f32_e32 v125, v125
	ds_read_u16 v126, v151 offset:9216
	ds_read_u16 v127, v152 offset:32
	ds_read_u16 v174, v152 offset:9248
	v_add_f32_e32 v120, 1.0, v120
	s_waitcnt lgkmcnt(3)
	v_lshlrev_b32_e32 v124, 16, v124
	v_mul_f32_e32 v124, v125, v124
	s_waitcnt lgkmcnt(2)
	v_lshlrev_b32_e32 v125, 16, v126
	v_rcp_f32_e32 v120, v120
	v_mul_f32_e32 v124, v124, v125
	v_cvt_pk_bf16_f32 v124, v124, s0
	ds_write_b16 v151, v124 offset:9216
	s_waitcnt lgkmcnt(2)
	v_lshlrev_b32_e32 v124, 16, v127
	v_mul_f32_e32 v120, v120, v124
	s_waitcnt lgkmcnt(1)
	v_lshlrev_b32_e32 v124, 16, v174
	v_mul_f32_e32 v121, 0xbfb8aa3b, v121
	v_mul_f32_e32 v120, v120, v124
	v_exp_f32_e32 v121, v121
	v_cvt_pk_bf16_f32 v120, v120, s0
	ds_write_b16 v152, v120 offset:9248
	ds_read_u16 v120, v147 offset:176
	v_add_f32_e32 v121, 1.0, v121
	ds_read_u16 v124, v147 offset:9392
	v_rcp_f32_e32 v121, v121
	v_add_f32_e32 v122, v122, v144
	v_mul_f32_e32 v122, 0xbfb8aa3b, v122
	s_waitcnt lgkmcnt(1)
	v_lshlrev_b32_e32 v120, 16, v120
	v_exp_f32_e32 v122, v122
	v_mul_f32_e32 v120, v121, v120
	s_waitcnt lgkmcnt(0)
	v_lshlrev_b32_e32 v121, 16, v124
	v_mul_f32_e32 v120, v120, v121
	v_cvt_pk_bf16_f32 v120, v120, s0
	ds_write_b16 v147, v120 offset:9392
	v_add_f32_e32 v120, 1.0, v122
	v_rcp_f32_e32 v120, v120
	ds_read_u16 v121, v150 offset:32
	ds_read_u16 v122, v150 offset:9248
	ds_read_u16 v124, v151 offset:32
	ds_read_u16 v125, v151 offset:9248
	ds_read_u16 v126, v152 offset:64
	ds_read_u16 v127, v152 offset:9280
	s_waitcnt lgkmcnt(5)
	v_lshlrev_b32_e32 v121, 16, v121
	v_add_f32_e32 v116, v116, v143
	v_mul_f32_e32 v120, v120, v121
	s_waitcnt lgkmcnt(4)
	v_lshlrev_b32_e32 v121, 16, v122
	v_mul_f32_e32 v120, v120, v121
	v_add_f32_e32 v121, v123, v144
	v_mul_f32_e32 v121, 0xbfb8aa3b, v121
	v_exp_f32_e32 v121, v121
	v_mul_f32_e32 v116, 0xbfb8aa3b, v116
	v_exp_f32_e32 v116, v116
	v_cvt_pk_bf16_f32 v120, v120, s0
	v_add_f32_e32 v121, 1.0, v121
	v_rcp_f32_e32 v121, v121
	ds_write_b16 v150, v120 offset:9248
	s_waitcnt lgkmcnt(4)
	v_lshlrev_b32_e32 v120, 16, v124
	v_add_f32_e32 v116, 1.0, v116
	v_mul_f32_e32 v120, v121, v120
	s_waitcnt lgkmcnt(3)
	v_lshlrev_b32_e32 v121, 16, v125
	v_rcp_f32_e32 v116, v116
	v_mul_f32_e32 v120, v120, v121
	v_cvt_pk_bf16_f32 v120, v120, s0
	ds_write_b16 v151, v120 offset:9248
	s_waitcnt lgkmcnt(3)
	v_lshlrev_b32_e32 v120, 16, v126
	v_add_f32_e32 v117, v117, v143
	v_mul_f32_e32 v116, v116, v120
	s_waitcnt lgkmcnt(2)
	v_lshlrev_b32_e32 v120, 16, v127
	v_mul_f32_e32 v117, 0xbfb8aa3b, v117
	v_mul_f32_e32 v116, v116, v120
	v_exp_f32_e32 v117, v117
	v_cvt_pk_bf16_f32 v116, v116, s0
	ds_write_b16 v152, v116 offset:9280
	ds_read_u16 v116, v147 offset:208
	v_add_f32_e32 v117, 1.0, v117
	ds_read_u16 v120, v147 offset:9424
	v_rcp_f32_e32 v117, v117
	v_add_f32_e32 v118, v118, v143
	v_mul_f32_e32 v118, 0xbfb8aa3b, v118
	s_waitcnt lgkmcnt(1)
	v_lshlrev_b32_e32 v116, 16, v116
	v_exp_f32_e32 v118, v118
	v_mul_f32_e32 v116, v117, v116
	s_waitcnt lgkmcnt(0)
	v_lshlrev_b32_e32 v117, 16, v120
	v_mul_f32_e32 v116, v116, v117
	v_cvt_pk_bf16_f32 v116, v116, s0
	ds_write_b16 v147, v116 offset:9424
	v_add_f32_e32 v116, 1.0, v118
	v_rcp_f32_e32 v116, v116
	ds_read_u16 v117, v150 offset:64
	ds_read_u16 v118, v150 offset:9280
	ds_read_u16 v120, v151 offset:64
	ds_read_u16 v121, v151 offset:9280
	ds_read_u16 v122, v152 offset:96
	ds_read_u16 v123, v152 offset:9312
	s_waitcnt lgkmcnt(5)
	v_lshlrev_b32_e32 v117, 16, v117
	v_add_f32_e32 v112, v112, v142
	v_mul_f32_e32 v116, v116, v117
	s_waitcnt lgkmcnt(4)
	v_lshlrev_b32_e32 v117, 16, v118
	v_mul_f32_e32 v116, v116, v117
	v_add_f32_e32 v117, v119, v143
	v_mul_f32_e32 v117, 0xbfb8aa3b, v117
	v_exp_f32_e32 v117, v117
	v_mul_f32_e32 v112, 0xbfb8aa3b, v112
	v_exp_f32_e32 v112, v112
	v_cvt_pk_bf16_f32 v116, v116, s0
	v_add_f32_e32 v117, 1.0, v117
	v_rcp_f32_e32 v117, v117
	ds_write_b16 v150, v116 offset:9280
	s_waitcnt lgkmcnt(4)
	v_lshlrev_b32_e32 v116, 16, v120
	v_add_f32_e32 v112, 1.0, v112
	v_mul_f32_e32 v116, v117, v116
	s_waitcnt lgkmcnt(3)
	v_lshlrev_b32_e32 v117, 16, v121
	v_rcp_f32_e32 v112, v112
	v_mul_f32_e32 v116, v116, v117
	v_cvt_pk_bf16_f32 v116, v116, s0
	ds_write_b16 v151, v116 offset:9280
	s_waitcnt lgkmcnt(3)
	v_lshlrev_b32_e32 v116, 16, v122
	v_add_f32_e32 v113, v113, v142
	v_mul_f32_e32 v112, v112, v116
	s_waitcnt lgkmcnt(2)
	v_lshlrev_b32_e32 v116, 16, v123
	v_mul_f32_e32 v113, 0xbfb8aa3b, v113
	v_mul_f32_e32 v112, v112, v116
	v_exp_f32_e32 v113, v113
	v_cvt_pk_bf16_f32 v112, v112, s0
	ds_write_b16 v152, v112 offset:9312
	ds_read_u16 v112, v147 offset:240
	v_add_f32_e32 v113, 1.0, v113
	ds_read_u16 v116, v147 offset:9456
	v_rcp_f32_e32 v113, v113
	v_add_f32_e32 v115, v115, v142
	s_waitcnt lgkmcnt(1)
	v_lshlrev_b32_e32 v112, 16, v112
	v_mul_f32_e32 v115, 0xbfb8aa3b, v115
	v_mul_f32_e32 v112, v113, v112
	s_waitcnt lgkmcnt(0)
	v_lshlrev_b32_e32 v113, 16, v116
	v_mul_f32_e32 v112, v112, v113
	v_add_f32_e32 v113, v114, v142
	v_mul_f32_e32 v113, 0xbfb8aa3b, v113
	v_exp_f32_e32 v113, v113
	v_cvt_pk_bf16_f32 v112, v112, s0
	ds_write_b16 v147, v112 offset:9456
	ds_read_u16 v112, v150 offset:96
	v_add_f32_e32 v113, 1.0, v113
	v_rcp_f32_e32 v113, v113
	ds_read_u16 v114, v150 offset:9312
	ds_read_u16 v116, v151 offset:96
	ds_read_u16 v117, v151 offset:9312
	v_exp_f32_e32 v115, v115
	s_waitcnt lgkmcnt(3)
	v_lshlrev_b32_e32 v112, 16, v112
	v_mul_f32_e32 v112, v113, v112
	s_waitcnt lgkmcnt(2)
	v_lshlrev_b32_e32 v113, 16, v114
	v_mul_f32_e32 v112, v112, v113
	v_add_f32_e32 v113, 1.0, v115
	v_rcp_f32_e32 v113, v113
	v_cvt_pk_bf16_f32 v112, v112, s0
	ds_write_b16 v150, v112 offset:9312
	s_waitcnt lgkmcnt(2)
	v_lshlrev_b32_e32 v112, 16, v116
	v_add_f32_e32 v108, v108, v145
	v_mul_f32_e32 v112, v113, v112
	s_waitcnt lgkmcnt(1)
	v_lshlrev_b32_e32 v113, 16, v117
	v_mul_f32_e32 v108, 0xbfb8aa3b, v108
	v_mul_f32_e32 v112, v112, v113
	v_exp_f32_e32 v108, v108
	v_cvt_pk_bf16_f32 v112, v112, s0
	ds_write_b16 v151, v112 offset:9312
	ds_read_u16 v112, v153
	v_add_f32_e32 v108, 1.0, v108
	ds_read_u16 v113, v153 offset:9216
	v_rcp_f32_e32 v108, v108
	v_add_f32_e32 v109, v109, v145
	s_waitcnt lgkmcnt(1)
	v_lshlrev_b32_e32 v112, 16, v112
	v_mul_f32_e32 v109, 0xbfb8aa3b, v109
	v_mul_f32_e32 v108, v108, v112
	s_waitcnt lgkmcnt(0)
	v_lshlrev_b32_e32 v112, 16, v113
	v_mul_f32_e32 v108, v108, v112
	v_exp_f32_e32 v109, v109
	v_cvt_pk_bf16_f32 v108, v108, s0
	ds_write_b16 v153, v108 offset:9216
	ds_read_u16 v108, v155
	v_add_f32_e32 v109, 1.0, v109
	ds_read_u16 v112, v155 offset:9216
	v_rcp_f32_e32 v109, v109
	v_add_f32_e32 v104, v104, v144
	s_waitcnt lgkmcnt(1)
	v_lshlrev_b32_e32 v108, 16, v108
	v_mul_f32_e32 v104, 0xbfb8aa3b, v104
	v_mul_f32_e32 v108, v109, v108
	s_waitcnt lgkmcnt(0)
	v_lshlrev_b32_e32 v109, 16, v112
	v_mul_f32_e32 v108, v108, v109
	v_add_f32_e32 v109, v110, v145
	v_mul_f32_e32 v109, 0xbfb8aa3b, v109
	v_exp_f32_e32 v109, v109
	v_cvt_pk_bf16_f32 v108, v108, s0
	ds_write_b16 v155, v108 offset:9216
	ds_read_u16 v108, v156
	v_add_f32_e32 v109, 1.0, v109
	ds_read_u16 v110, v156 offset:9216
	v_rcp_f32_e32 v109, v109
	v_exp_f32_e32 v104, v104
	s_waitcnt lgkmcnt(1)
	v_lshlrev_b32_e32 v108, 16, v108
	v_add_f32_e32 v106, v106, v144
	v_mul_f32_e32 v108, v109, v108
	s_waitcnt lgkmcnt(0)
	v_lshlrev_b32_e32 v109, 16, v110
	v_mul_f32_e32 v108, v108, v109
	v_add_f32_e32 v109, v111, v145
	v_mul_f32_e32 v109, 0xbfb8aa3b, v109
	v_exp_f32_e32 v109, v109
	v_cvt_pk_bf16_f32 v108, v108, s0
	ds_write_b16 v156, v108 offset:9216
	ds_read_u16 v108, v158
	v_add_f32_e32 v109, 1.0, v109
	v_rcp_f32_e32 v109, v109
	ds_read_u16 v110, v158 offset:32
	ds_read_u16 v111, v155 offset:9312
	v_add_f32_e32 v104, 1.0, v104
	s_waitcnt lgkmcnt(2)
	v_lshlrev_b32_e32 v108, 16, v108
	v_mul_f32_e32 v108, v109, v108
	ds_read_u16 v109, v158 offset:9216
	ds_read_u16 v112, v154 offset:32
	ds_read_u16 v113, v154 offset:64
	ds_read_u16 v114, v158 offset:9248
	ds_read_u16 v115, v158 offset:64
	ds_read_u16 v116, v158 offset:9280
	ds_read_u16 v117, v158 offset:9312
	ds_read_u16 v118, v158 offset:96
	s_waitcnt lgkmcnt(7)
	v_lshlrev_b32_e32 v109, 16, v109
	v_rcp_f32_e32 v104, v104
	v_mul_f32_e32 v108, v108, v109
	v_cvt_pk_bf16_f32 v108, v108, s0
	ds_write_b16 v158, v108 offset:9216
	s_waitcnt lgkmcnt(7)
	v_lshlrev_b32_e32 v108, 16, v112
	v_mul_f32_e32 v104, v104, v108
	ds_read_u16 v108, v154 offset:9248
	ds_read_u16 v109, v157 offset:32
	ds_read_u16 v112, v157 offset:9248
	ds_read_u16 v119, v154 offset:9280
	ds_read_u16 v120, v157 offset:64
	ds_read_u16 v121, v157 offset:96
	ds_read_u16 v122, v154 offset:9312
	ds_read_u16 v123, v154 offset:96
	s_waitcnt lgkmcnt(7)
	v_lshlrev_b32_e32 v108, 16, v108
	v_mul_f32_e32 v104, v104, v108
	v_cvt_pk_bf16_f32 v104, v104, s0
	ds_write_b16 v154, v104 offset:9248
	v_add_f32_e32 v104, v105, v144
	v_mul_f32_e32 v104, 0xbfb8aa3b, v104
	v_exp_f32_e32 v104, v104
	v_mul_f32_e32 v106, 0xbfb8aa3b, v106
	v_exp_f32_e32 v106, v106
	ds_read_u16 v105, v155 offset:32
	ds_read_u16 v108, v155 offset:9248
	ds_read_u16 v124, v155 offset:9280
	ds_read_u16 v125, v155 offset:64
	ds_read_u16 v126, v155 offset:96
	v_add_f32_e32 v104, 1.0, v104
	v_rcp_f32_e32 v104, v104
	s_waitcnt lgkmcnt(4)
	v_lshlrev_b32_e32 v105, 16, v105
	v_add_f32_e32 v100, v100, v143
	v_mul_f32_e32 v100, 0xbfb8aa3b, v100
	v_mul_f32_e32 v104, v104, v105
	s_waitcnt lgkmcnt(3)
	v_lshlrev_b32_e32 v105, 16, v108
	v_mul_f32_e32 v104, v104, v105
	v_add_f32_e32 v105, 1.0, v106
	v_rcp_f32_e32 v105, v105
	v_cvt_pk_bf16_f32 v104, v104, s0
	ds_write_b16 v155, v104 offset:9248
	v_lshlrev_b32_e32 v104, 16, v109
	v_mul_f32_e32 v104, v105, v104
	v_lshlrev_b32_e32 v105, 16, v112
	v_mul_f32_e32 v104, v104, v105
	v_add_f32_e32 v105, v107, v144
	v_mul_f32_e32 v105, 0xbfb8aa3b, v105
	v_exp_f32_e32 v105, v105
	v_exp_f32_e32 v100, v100
	v_add_f32_e32 v101, v101, v143
	v_cvt_pk_bf16_f32 v104, v104, s0
	v_add_f32_e32 v105, 1.0, v105
	v_rcp_f32_e32 v105, v105
	v_mul_f32_e32 v101, 0xbfb8aa3b, v101
	ds_write_b16 v157, v104 offset:9248
	v_lshlrev_b32_e32 v104, 16, v110
	v_add_f32_e32 v100, 1.0, v100
	v_exp_f32_e32 v101, v101
	v_mul_f32_e32 v104, v105, v104
	v_lshlrev_b32_e32 v105, 16, v114
	v_rcp_f32_e32 v100, v100
	v_mul_f32_e32 v104, v104, v105
	v_cvt_pk_bf16_f32 v104, v104, s0
	ds_write_b16 v158, v104 offset:9248
	v_lshlrev_b32_e32 v104, 16, v113
	v_add_f32_e32 v101, 1.0, v101
	v_add_f32_e32 v102, v102, v143
	v_mul_f32_e32 v100, v100, v104
	v_lshlrev_b32_e32 v104, 16, v119
	v_rcp_f32_e32 v101, v101
	v_mul_f32_e32 v102, 0xbfb8aa3b, v102
	v_mul_f32_e32 v100, v100, v104
	v_exp_f32_e32 v102, v102
	v_cvt_pk_bf16_f32 v100, v100, s0
	ds_write_b16 v154, v100 offset:9280
	s_waitcnt lgkmcnt(5)
	v_lshlrev_b32_e32 v100, 16, v125
	v_mul_f32_e32 v100, v101, v100
	v_lshlrev_b32_e32 v101, 16, v124
	v_mul_f32_e32 v100, v100, v101
	v_add_f32_e32 v101, 1.0, v102
	v_rcp_f32_e32 v101, v101
	v_cvt_pk_bf16_f32 v100, v100, s0
	ds_write_b16 v155, v100 offset:9280
	v_lshlrev_b32_e32 v100, 16, v120
	v_mul_f32_e32 v100, v101, v100
	ds_read_u16 v101, v157 offset:9280
	v_add_f32_e32 v102, v103, v143
	v_mul_f32_e32 v102, 0xbfb8aa3b, v102
	v_exp_f32_e32 v102, v102
	v_add_f32_e32 v96, v96, v142
	s_waitcnt lgkmcnt(0)
	v_lshlrev_b32_e32 v101, 16, v101
	v_mul_f32_e32 v96, 0xbfb8aa3b, v96
	v_mul_f32_e32 v100, v100, v101
	v_add_f32_e32 v101, 1.0, v102
	v_exp_f32_e32 v96, v96
	v_rcp_f32_e32 v101, v101
	v_add_f32_e32 v97, v97, v142
	v_cvt_pk_bf16_f32 v100, v100, s0
	v_mul_f32_e32 v97, 0xbfb8aa3b, v97
	ds_write_b16 v157, v100 offset:9280
	v_lshlrev_b32_e32 v100, 16, v115
	v_add_f32_e32 v96, 1.0, v96
	v_exp_f32_e32 v97, v97
	v_mul_f32_e32 v100, v101, v100
	v_lshlrev_b32_e32 v101, 16, v116
	v_rcp_f32_e32 v96, v96
	v_mul_f32_e32 v100, v100, v101
	v_cvt_pk_bf16_f32 v100, v100, s0
	ds_write_b16 v158, v100 offset:9280
	v_lshlrev_b32_e32 v100, 16, v123
	v_add_f32_e32 v97, 1.0, v97
	v_mul_f32_e32 v96, v96, v100
	v_lshlrev_b32_e32 v100, 16, v122
	v_rcp_f32_e32 v97, v97
	v_mul_f32_e32 v96, v96, v100
	v_cvt_pk_bf16_f32 v96, v96, s0
	ds_write_b16 v154, v96 offset:9312
	v_lshlrev_b32_e32 v96, 16, v126
	v_mul_f32_e32 v96, v97, v96
	v_lshlrev_b32_e32 v97, 16, v111
	v_mul_f32_e32 v96, v96, v97
	v_add_f32_e32 v97, v98, v142
	v_mul_f32_e32 v97, 0xbfb8aa3b, v97
	v_exp_f32_e32 v97, v97
	ds_read_u16 v103, v157 offset:9312
	v_add_f32_e32 v98, v99, v142
	v_mul_f32_e32 v98, 0xbfb8aa3b, v98
	v_add_f32_e32 v97, 1.0, v97
	v_rcp_f32_e32 v97, v97
	v_exp_f32_e32 v98, v98
	v_cvt_pk_bf16_f32 v96, v96, s0
	ds_write_b16 v155, v96 offset:9312
	v_lshlrev_b32_e32 v96, 16, v121
	v_mul_f32_e32 v96, v97, v96
	s_waitcnt lgkmcnt(1)
	v_lshlrev_b32_e32 v97, 16, v103
	v_mul_f32_e32 v96, v96, v97
	v_add_f32_e32 v97, 1.0, v98
	v_rcp_f32_e32 v97, v97
	v_cvt_pk_bf16_f32 v96, v96, s0
	ds_write_b16 v157, v96 offset:9312
	v_lshlrev_b32_e32 v96, 16, v118
	v_add_f32_e32 v92, v92, v145
	v_mul_f32_e32 v96, v97, v96
	v_lshlrev_b32_e32 v97, 16, v117
	v_mul_f32_e32 v92, 0xbfb8aa3b, v92
	v_mul_f32_e32 v96, v96, v97
	v_exp_f32_e32 v92, v92
	v_cvt_pk_bf16_f32 v96, v96, s0
	ds_write_b16 v158, v96 offset:9312
	ds_read_u16 v96, v159
	v_add_f32_e32 v92, 1.0, v92
	ds_read_u16 v97, v159 offset:9216
	v_rcp_f32_e32 v92, v92
	v_add_f32_e32 v93, v93, v145
	s_waitcnt lgkmcnt(1)
	v_lshlrev_b32_e32 v96, 16, v96
	v_mul_f32_e32 v93, 0xbfb8aa3b, v93
	v_mul_f32_e32 v92, v92, v96
	s_waitcnt lgkmcnt(0)
	v_lshlrev_b32_e32 v96, 16, v97
	v_mul_f32_e32 v92, v92, v96
	v_exp_f32_e32 v93, v93
	v_cvt_pk_bf16_f32 v92, v92, s0
	ds_write_b16 v159, v92 offset:9216
	ds_read_u16 v92, v161
	v_add_f32_e32 v93, 1.0, v93
	ds_read_u16 v96, v161 offset:9216
	v_rcp_f32_e32 v93, v93
	v_add_f32_e32 v88, v88, v144
	s_waitcnt lgkmcnt(1)
	v_lshlrev_b32_e32 v92, 16, v92
	v_mul_f32_e32 v88, 0xbfb8aa3b, v88
	v_mul_f32_e32 v92, v93, v92
	s_waitcnt lgkmcnt(0)
	v_lshlrev_b32_e32 v93, 16, v96
	v_mul_f32_e32 v92, v92, v93
	v_add_f32_e32 v93, v94, v145
	v_mul_f32_e32 v93, 0xbfb8aa3b, v93
	v_exp_f32_e32 v93, v93
	v_cvt_pk_bf16_f32 v92, v92, s0
	ds_write_b16 v161, v92 offset:9216
	ds_read_u16 v92, v162
	v_add_f32_e32 v93, 1.0, v93
	ds_read_u16 v94, v162 offset:9216
	v_rcp_f32_e32 v93, v93
	v_exp_f32_e32 v88, v88
	s_waitcnt lgkmcnt(1)
	v_lshlrev_b32_e32 v92, 16, v92
	v_add_f32_e32 v90, v90, v144
	v_mul_f32_e32 v92, v93, v92
	s_waitcnt lgkmcnt(0)
	v_lshlrev_b32_e32 v93, 16, v94
	v_mul_f32_e32 v92, v92, v93
	v_add_f32_e32 v93, v95, v145
	v_mul_f32_e32 v93, 0xbfb8aa3b, v93
	v_exp_f32_e32 v93, v93
	v_cvt_pk_bf16_f32 v92, v92, s0
	ds_write_b16 v162, v92 offset:9216
	ds_read_u16 v92, v164
	v_add_f32_e32 v93, 1.0, v93
	v_rcp_f32_e32 v93, v93
	ds_read_u16 v94, v164 offset:32
	ds_read_u16 v95, v161 offset:9312
	v_add_f32_e32 v88, 1.0, v88
	s_waitcnt lgkmcnt(2)
	v_lshlrev_b32_e32 v92, 16, v92
	v_mul_f32_e32 v92, v93, v92
	ds_read_u16 v93, v164 offset:9216
	ds_read_u16 v96, v160 offset:32
	ds_read_u16 v97, v160 offset:64
	ds_read_u16 v98, v164 offset:9248
	ds_read_u16 v99, v164 offset:64
	ds_read_u16 v100, v164 offset:9280
	ds_read_u16 v101, v164 offset:9312
	ds_read_u16 v102, v164 offset:96
	s_waitcnt lgkmcnt(7)
	v_lshlrev_b32_e32 v93, 16, v93
	v_rcp_f32_e32 v88, v88
	v_mul_f32_e32 v92, v92, v93
	v_cvt_pk_bf16_f32 v92, v92, s0
	ds_write_b16 v164, v92 offset:9216
	s_waitcnt lgkmcnt(7)
	v_lshlrev_b32_e32 v92, 16, v96
	v_mul_f32_e32 v88, v88, v92
	ds_read_u16 v92, v160 offset:9248
	ds_read_u16 v93, v163 offset:32
	ds_read_u16 v96, v163 offset:9248
	ds_read_u16 v103, v160 offset:9280
	ds_read_u16 v104, v163 offset:64
	ds_read_u16 v105, v163 offset:96
	ds_read_u16 v106, v160 offset:9312
	ds_read_u16 v107, v160 offset:96
	s_waitcnt lgkmcnt(7)
	v_lshlrev_b32_e32 v92, 16, v92
	v_mul_f32_e32 v88, v88, v92
	v_cvt_pk_bf16_f32 v88, v88, s0
	ds_write_b16 v160, v88 offset:9248
	v_add_f32_e32 v88, v89, v144
	v_mul_f32_e32 v88, 0xbfb8aa3b, v88
	v_exp_f32_e32 v88, v88
	v_mul_f32_e32 v90, 0xbfb8aa3b, v90
	v_exp_f32_e32 v90, v90
	ds_read_u16 v89, v161 offset:32
	ds_read_u16 v92, v161 offset:9248
	ds_read_u16 v108, v161 offset:9280
	ds_read_u16 v109, v161 offset:64
	ds_read_u16 v110, v161 offset:96
	v_add_f32_e32 v88, 1.0, v88
	v_rcp_f32_e32 v88, v88
	s_waitcnt lgkmcnt(4)
	v_lshlrev_b32_e32 v89, 16, v89
	v_add_f32_e32 v84, v84, v143
	v_mul_f32_e32 v84, 0xbfb8aa3b, v84
	v_mul_f32_e32 v88, v88, v89
	s_waitcnt lgkmcnt(3)
	v_lshlrev_b32_e32 v89, 16, v92
	v_mul_f32_e32 v88, v88, v89
	v_add_f32_e32 v89, 1.0, v90
	v_rcp_f32_e32 v89, v89
	v_cvt_pk_bf16_f32 v88, v88, s0
	ds_write_b16 v161, v88 offset:9248
	v_lshlrev_b32_e32 v88, 16, v93
	v_mul_f32_e32 v88, v89, v88
	v_lshlrev_b32_e32 v89, 16, v96
	v_mul_f32_e32 v88, v88, v89
	v_add_f32_e32 v89, v91, v144
	v_mul_f32_e32 v89, 0xbfb8aa3b, v89
	v_exp_f32_e32 v89, v89
	v_exp_f32_e32 v84, v84
	v_add_f32_e32 v85, v85, v143
	v_cvt_pk_bf16_f32 v88, v88, s0
	v_add_f32_e32 v89, 1.0, v89
	v_rcp_f32_e32 v89, v89
	v_mul_f32_e32 v85, 0xbfb8aa3b, v85
	ds_write_b16 v163, v88 offset:9248
	v_lshlrev_b32_e32 v88, 16, v94
	v_add_f32_e32 v84, 1.0, v84
	v_exp_f32_e32 v85, v85
	v_mul_f32_e32 v88, v89, v88
	v_lshlrev_b32_e32 v89, 16, v98
	v_rcp_f32_e32 v84, v84
	v_mul_f32_e32 v88, v88, v89
	v_cvt_pk_bf16_f32 v88, v88, s0
	ds_write_b16 v164, v88 offset:9248
	v_lshlrev_b32_e32 v88, 16, v97
	v_add_f32_e32 v85, 1.0, v85
	v_add_f32_e32 v86, v86, v143
	v_mul_f32_e32 v84, v84, v88
	v_lshlrev_b32_e32 v88, 16, v103
	v_rcp_f32_e32 v85, v85
	v_mul_f32_e32 v86, 0xbfb8aa3b, v86
	v_mul_f32_e32 v84, v84, v88
	v_exp_f32_e32 v86, v86
	v_cvt_pk_bf16_f32 v84, v84, s0
	ds_write_b16 v160, v84 offset:9280
	s_waitcnt lgkmcnt(5)
	v_lshlrev_b32_e32 v84, 16, v109
	v_mul_f32_e32 v84, v85, v84
	v_lshlrev_b32_e32 v85, 16, v108
	v_mul_f32_e32 v84, v84, v85
	v_add_f32_e32 v85, 1.0, v86
	v_rcp_f32_e32 v85, v85
	v_cvt_pk_bf16_f32 v84, v84, s0
	ds_write_b16 v161, v84 offset:9280
	v_lshlrev_b32_e32 v84, 16, v104
	v_mul_f32_e32 v84, v85, v84
	ds_read_u16 v85, v163 offset:9280
	v_add_f32_e32 v86, v87, v143
	v_mul_f32_e32 v86, 0xbfb8aa3b, v86
	v_exp_f32_e32 v86, v86
	v_add_f32_e32 v80, v80, v142
	s_waitcnt lgkmcnt(0)
	v_lshlrev_b32_e32 v85, 16, v85
	v_mul_f32_e32 v80, 0xbfb8aa3b, v80
	v_mul_f32_e32 v84, v84, v85
	v_add_f32_e32 v85, 1.0, v86
	v_exp_f32_e32 v80, v80
	v_rcp_f32_e32 v85, v85
	v_add_f32_e32 v81, v81, v142
	v_cvt_pk_bf16_f32 v84, v84, s0
	v_mul_f32_e32 v81, 0xbfb8aa3b, v81
	ds_write_b16 v163, v84 offset:9280
	v_lshlrev_b32_e32 v84, 16, v99
	v_add_f32_e32 v80, 1.0, v80
	v_exp_f32_e32 v81, v81
	v_mul_f32_e32 v84, v85, v84
	v_lshlrev_b32_e32 v85, 16, v100
	v_rcp_f32_e32 v80, v80
	v_mul_f32_e32 v84, v84, v85
	v_cvt_pk_bf16_f32 v84, v84, s0
	ds_write_b16 v164, v84 offset:9280
	v_lshlrev_b32_e32 v84, 16, v107
	v_add_f32_e32 v81, 1.0, v81
	v_mul_f32_e32 v80, v80, v84
	v_lshlrev_b32_e32 v84, 16, v106
	v_rcp_f32_e32 v81, v81
	v_mul_f32_e32 v80, v80, v84
	v_cvt_pk_bf16_f32 v80, v80, s0
	ds_write_b16 v160, v80 offset:9312
	v_lshlrev_b32_e32 v80, 16, v110
	v_mul_f32_e32 v80, v81, v80
	v_lshlrev_b32_e32 v81, 16, v95
	v_mul_f32_e32 v80, v80, v81
	v_add_f32_e32 v81, v82, v142
	v_mul_f32_e32 v81, 0xbfb8aa3b, v81
	v_exp_f32_e32 v81, v81
	ds_read_u16 v87, v163 offset:9312
	v_add_f32_e32 v82, v83, v142
	v_mul_f32_e32 v82, 0xbfb8aa3b, v82
	v_add_f32_e32 v81, 1.0, v81
	v_rcp_f32_e32 v81, v81
	v_exp_f32_e32 v82, v82
	v_cvt_pk_bf16_f32 v80, v80, s0
	ds_write_b16 v161, v80 offset:9312
	v_lshlrev_b32_e32 v80, 16, v105
	v_mul_f32_e32 v80, v81, v80
	s_waitcnt lgkmcnt(1)
	v_lshlrev_b32_e32 v81, 16, v87
	v_mul_f32_e32 v80, v80, v81
	v_add_f32_e32 v81, 1.0, v82
	v_rcp_f32_e32 v81, v81
	v_cvt_pk_bf16_f32 v80, v80, s0
	ds_write_b16 v163, v80 offset:9312
	v_lshlrev_b32_e32 v80, 16, v102
	v_add_f32_e32 v76, v76, v145
	v_mul_f32_e32 v80, v81, v80
	v_lshlrev_b32_e32 v81, 16, v101
	v_mul_f32_e32 v76, 0xbfb8aa3b, v76
	v_mul_f32_e32 v80, v80, v81
	v_exp_f32_e32 v76, v76
	v_cvt_pk_bf16_f32 v80, v80, s0
	ds_write_b16 v164, v80 offset:9312
	ds_read_u16 v80, v165
	v_add_f32_e32 v76, 1.0, v76
	ds_read_u16 v81, v165 offset:9216
	v_rcp_f32_e32 v76, v76
	v_add_f32_e32 v77, v77, v145
	s_waitcnt lgkmcnt(1)
	v_lshlrev_b32_e32 v80, 16, v80
	v_mul_f32_e32 v77, 0xbfb8aa3b, v77
	v_mul_f32_e32 v76, v76, v80
	s_waitcnt lgkmcnt(0)
	v_lshlrev_b32_e32 v80, 16, v81
	v_mul_f32_e32 v76, v76, v80
	v_exp_f32_e32 v77, v77
	v_cvt_pk_bf16_f32 v76, v76, s0
	ds_write_b16 v165, v76 offset:9216
	ds_read_u16 v76, v167
	v_add_f32_e32 v77, 1.0, v77
	ds_read_u16 v80, v167 offset:9216
	v_rcp_f32_e32 v77, v77
	v_add_f32_e32 v72, v72, v144
	s_waitcnt lgkmcnt(1)
	v_lshlrev_b32_e32 v76, 16, v76
	v_mul_f32_e32 v72, 0xbfb8aa3b, v72
	v_mul_f32_e32 v76, v77, v76
	s_waitcnt lgkmcnt(0)
	v_lshlrev_b32_e32 v77, 16, v80
	v_mul_f32_e32 v76, v76, v77
	v_add_f32_e32 v77, v78, v145
	v_mul_f32_e32 v77, 0xbfb8aa3b, v77
	v_exp_f32_e32 v77, v77
	v_cvt_pk_bf16_f32 v76, v76, s0
	ds_write_b16 v167, v76 offset:9216
	ds_read_u16 v76, v168
	v_add_f32_e32 v77, 1.0, v77
	ds_read_u16 v78, v168 offset:9216
	v_rcp_f32_e32 v77, v77
	v_exp_f32_e32 v72, v72
	s_waitcnt lgkmcnt(1)
	v_lshlrev_b32_e32 v76, 16, v76
	v_add_f32_e32 v74, v74, v144
	v_mul_f32_e32 v76, v77, v76
	s_waitcnt lgkmcnt(0)
	v_lshlrev_b32_e32 v77, 16, v78
	v_mul_f32_e32 v76, v76, v77
	v_add_f32_e32 v77, v79, v145
	v_mul_f32_e32 v77, 0xbfb8aa3b, v77
	v_exp_f32_e32 v77, v77
	v_cvt_pk_bf16_f32 v76, v76, s0
	ds_write_b16 v168, v76 offset:9216
	ds_read_u16 v76, v170
	v_add_f32_e32 v77, 1.0, v77
	v_rcp_f32_e32 v77, v77
	ds_read_u16 v78, v170 offset:32
	ds_read_u16 v79, v167 offset:9312
	v_add_f32_e32 v72, 1.0, v72
	s_waitcnt lgkmcnt(2)
	v_lshlrev_b32_e32 v76, 16, v76
	v_mul_f32_e32 v76, v77, v76
	ds_read_u16 v77, v170 offset:9216
	ds_read_u16 v80, v166 offset:32
	ds_read_u16 v81, v166 offset:64
	ds_read_u16 v82, v170 offset:9248
	ds_read_u16 v83, v170 offset:64
	ds_read_u16 v84, v170 offset:9280
	ds_read_u16 v85, v170 offset:9312
	ds_read_u16 v86, v170 offset:96
	s_waitcnt lgkmcnt(7)
	v_lshlrev_b32_e32 v77, 16, v77
	v_rcp_f32_e32 v72, v72
	v_mul_f32_e32 v76, v76, v77
	v_cvt_pk_bf16_f32 v76, v76, s0
	ds_write_b16 v170, v76 offset:9216
	s_waitcnt lgkmcnt(7)
	v_lshlrev_b32_e32 v76, 16, v80
	v_mul_f32_e32 v72, v72, v76
	ds_read_u16 v76, v166 offset:9248
	ds_read_u16 v77, v169 offset:32
	ds_read_u16 v80, v169 offset:9248
	ds_read_u16 v87, v166 offset:9280
	ds_read_u16 v88, v169 offset:64
	ds_read_u16 v89, v169 offset:96
	ds_read_u16 v90, v166 offset:9312
	ds_read_u16 v91, v166 offset:96
	s_waitcnt lgkmcnt(7)
	v_lshlrev_b32_e32 v76, 16, v76
	v_mul_f32_e32 v72, v72, v76
	v_cvt_pk_bf16_f32 v72, v72, s0
	ds_write_b16 v166, v72 offset:9248
	v_add_f32_e32 v72, v73, v144
	v_mul_f32_e32 v72, 0xbfb8aa3b, v72
	v_exp_f32_e32 v72, v72
	v_mul_f32_e32 v74, 0xbfb8aa3b, v74
	v_exp_f32_e32 v74, v74
	ds_read_u16 v73, v167 offset:32
	ds_read_u16 v76, v167 offset:9248
	ds_read_u16 v92, v167 offset:9280
	ds_read_u16 v93, v167 offset:64
	ds_read_u16 v94, v167 offset:96
	v_add_f32_e32 v72, 1.0, v72
	v_rcp_f32_e32 v72, v72
	s_waitcnt lgkmcnt(4)
	v_lshlrev_b32_e32 v73, 16, v73
	v_add_f32_e32 v68, v68, v143
	v_mul_f32_e32 v68, 0xbfb8aa3b, v68
	v_mul_f32_e32 v72, v72, v73
	s_waitcnt lgkmcnt(3)
	v_lshlrev_b32_e32 v73, 16, v76
	v_mul_f32_e32 v72, v72, v73
	v_add_f32_e32 v73, 1.0, v74
	v_rcp_f32_e32 v73, v73
	v_cvt_pk_bf16_f32 v72, v72, s0
	ds_write_b16 v167, v72 offset:9248
	v_lshlrev_b32_e32 v72, 16, v77
	v_mul_f32_e32 v72, v73, v72
	v_lshlrev_b32_e32 v73, 16, v80
	v_mul_f32_e32 v72, v72, v73
	v_add_f32_e32 v73, v75, v144
	v_mul_f32_e32 v73, 0xbfb8aa3b, v73
	v_exp_f32_e32 v73, v73
	v_exp_f32_e32 v68, v68
	v_add_f32_e32 v69, v69, v143
	v_cvt_pk_bf16_f32 v72, v72, s0
	v_add_f32_e32 v73, 1.0, v73
	v_rcp_f32_e32 v73, v73
	v_mul_f32_e32 v69, 0xbfb8aa3b, v69
	ds_write_b16 v169, v72 offset:9248
	v_lshlrev_b32_e32 v72, 16, v78
	v_add_f32_e32 v68, 1.0, v68
	v_exp_f32_e32 v69, v69
	v_mul_f32_e32 v72, v73, v72
	v_lshlrev_b32_e32 v73, 16, v82
	v_rcp_f32_e32 v68, v68
	v_mul_f32_e32 v72, v72, v73
	v_cvt_pk_bf16_f32 v72, v72, s0
	ds_write_b16 v170, v72 offset:9248
	v_lshlrev_b32_e32 v72, 16, v81
	v_add_f32_e32 v69, 1.0, v69
	v_add_f32_e32 v70, v70, v143
	v_mul_f32_e32 v68, v68, v72
	v_lshlrev_b32_e32 v72, 16, v87
	v_rcp_f32_e32 v69, v69
	v_mul_f32_e32 v70, 0xbfb8aa3b, v70
	v_mul_f32_e32 v68, v68, v72
	v_exp_f32_e32 v70, v70
	v_cvt_pk_bf16_f32 v68, v68, s0
	ds_write_b16 v166, v68 offset:9280
	s_waitcnt lgkmcnt(5)
	v_lshlrev_b32_e32 v68, 16, v93
	v_mul_f32_e32 v68, v69, v68
	v_lshlrev_b32_e32 v69, 16, v92
	v_mul_f32_e32 v68, v68, v69
	v_add_f32_e32 v69, 1.0, v70
	v_rcp_f32_e32 v69, v69
	v_cvt_pk_bf16_f32 v68, v68, s0
	ds_write_b16 v167, v68 offset:9280
	v_lshlrev_b32_e32 v68, 16, v88
	v_mul_f32_e32 v68, v69, v68
	ds_read_u16 v69, v169 offset:9280
	v_add_f32_e32 v70, v71, v143
	v_mul_f32_e32 v70, 0xbfb8aa3b, v70
	v_exp_f32_e32 v70, v70
	v_add_f32_e32 v64, v64, v142
	s_waitcnt lgkmcnt(0)
	v_lshlrev_b32_e32 v69, 16, v69
	v_mul_f32_e32 v64, 0xbfb8aa3b, v64
	v_mul_f32_e32 v68, v68, v69
	v_add_f32_e32 v69, 1.0, v70
	v_exp_f32_e32 v64, v64
	v_rcp_f32_e32 v69, v69
	v_add_f32_e32 v65, v65, v142
	v_cvt_pk_bf16_f32 v68, v68, s0
	v_mul_f32_e32 v65, 0xbfb8aa3b, v65
	ds_write_b16 v169, v68 offset:9280
	v_lshlrev_b32_e32 v68, 16, v83
	v_add_f32_e32 v64, 1.0, v64
	v_exp_f32_e32 v65, v65
	v_mul_f32_e32 v68, v69, v68
	v_lshlrev_b32_e32 v69, 16, v84
	v_rcp_f32_e32 v64, v64
	v_mul_f32_e32 v68, v68, v69
	v_cvt_pk_bf16_f32 v68, v68, s0
	ds_write_b16 v170, v68 offset:9280
	v_lshlrev_b32_e32 v68, 16, v91
	v_add_f32_e32 v65, 1.0, v65
	v_mul_f32_e32 v64, v64, v68
	v_lshlrev_b32_e32 v68, 16, v90
	v_rcp_f32_e32 v65, v65
	v_mul_f32_e32 v64, v64, v68
	v_cvt_pk_bf16_f32 v64, v64, s0
	ds_write_b16 v166, v64 offset:9312
	v_lshlrev_b32_e32 v64, 16, v94
	v_mul_f32_e32 v64, v65, v64
	v_lshlrev_b32_e32 v65, 16, v79
	v_mul_f32_e32 v64, v64, v65
	v_add_f32_e32 v65, v66, v142
	v_mul_f32_e32 v65, 0xbfb8aa3b, v65
	v_exp_f32_e32 v65, v65
	ds_read_u16 v71, v169 offset:9312
	v_add_f32_e32 v66, v67, v142
	v_mul_f32_e32 v66, 0xbfb8aa3b, v66
	v_add_f32_e32 v65, 1.0, v65
	v_rcp_f32_e32 v65, v65
	v_exp_f32_e32 v66, v66
	v_cvt_pk_bf16_f32 v64, v64, s0
	ds_write_b16 v167, v64 offset:9312
	v_lshlrev_b32_e32 v64, 16, v89
	v_mul_f32_e32 v64, v65, v64
	s_waitcnt lgkmcnt(1)
	v_lshlrev_b32_e32 v65, 16, v71
	v_mul_f32_e32 v64, v64, v65
	v_add_f32_e32 v65, 1.0, v66
	v_rcp_f32_e32 v65, v65
	v_cvt_pk_bf16_f32 v64, v64, s0
	ds_write_b16 v169, v64 offset:9312
	v_lshlrev_b32_e32 v64, 16, v86
	v_mul_f32_e32 v64, v65, v64
	v_lshlrev_b32_e32 v65, 16, v85
	v_mul_f32_e32 v64, v64, v65
	v_cvt_pk_bf16_f32 v64, v64, s0
	ds_write_b16 v170, v64 offset:9312
	s_waitcnt lgkmcnt(0)
	s_mov_b64 s[64:65], 0
	v_mov_b32_e32 v64, v130
.LBB0_679:
	v_lshl_add_u64 v[82:83], v[140:141], 0, s[64:65]
	v_add_co_u32_e32 v84, vcc, 0x6000000, v82
	ds_read_b128 v[66:69], v64
	ds_read_b128 v[70:73], v64 offset:1152
	ds_read_b128 v[74:77], v64 offset:2304
	ds_read_b128 v[78:81], v64 offset:3456
	v_addc_co_u32_e32 v85, vcc, 0, v83, vcc
	v_add_co_u32_e32 v86, vcc, 0x6008000, v82
	s_add_u32 s64, s64, 0x20000
	s_nop 0
	v_addc_co_u32_e32 v87, vcc, 0, v83, vcc
	v_add_co_u32_e32 v88, vcc, 0x6010000, v82
	s_addc_u32 s65, s65, 0
	s_nop 0
	v_addc_co_u32_e32 v89, vcc, 0, v83, vcc
	v_add_co_u32_e32 v82, vcc, 0x6018000, v82
	v_add_u32_e32 v64, 0x1200, v64
	s_cmp_lg_u32 s64, 0x40000
	v_addc_co_u32_e32 v83, vcc, 0, v83, vcc
	s_waitcnt lgkmcnt(3)
	global_store_dwordx4 v[84:85], v[66:69], off sc1
	s_waitcnt lgkmcnt(2)
	global_store_dwordx4 v[86:87], v[70:73], off sc1
	s_waitcnt lgkmcnt(1)
	global_store_dwordx4 v[88:89], v[74:77], off sc1
	s_waitcnt lgkmcnt(0)
	global_store_dwordx4 v[82:83], v[78:81], off sc1
	s_cbranch_scc1 .LBB0_679
	s_waitcnt lgkmcnt(0)
	s_mov_b64 s[64:65], 0
	v_mov_b32_e32 v64, v171
	s_waitcnt vmcnt(13)
	ds_write_b128 v171, v[194:197]
	s_waitcnt vmcnt(12)
	ds_write_b128 v171, v[198:201] offset:1152
	s_mov_b64 s[64:65], 0x8000
	global_load_dwordx4 v[194:197], v[250:251], off
	v_lshl_add_u64 v[250:251], v[250:251], 0, s[64:65]
	global_load_dwordx4 v[198:201], v[250:251], off
	s_waitcnt vmcnt(13)
	ds_write_b128 v171, v[202:205] offset:2304
	s_waitcnt vmcnt(12)
	ds_write_b128 v171, v[206:209] offset:3456
	s_waitcnt vmcnt(11)
	ds_write_b128 v171, v[210:213] offset:4608
	s_waitcnt vmcnt(10)
	ds_write_b128 v171, v[214:217] offset:5760
	s_waitcnt vmcnt(9)
	ds_write_b128 v171, v[218:221] offset:6912
	s_waitcnt vmcnt(8)
	ds_write_b128 v171, v[222:225] offset:8064
	s_waitcnt vmcnt(7)
	ds_write_b128 v130, v[226:229]
	s_waitcnt vmcnt(6)
	ds_write_b128 v130, v[230:233] offset:1152
	s_waitcnt vmcnt(5)
	ds_write_b128 v130, v[234:237] offset:2304
	s_waitcnt vmcnt(4)
	ds_write_b128 v130, v[238:241] offset:3456
	s_waitcnt vmcnt(3)
	ds_write_b128 v130, v[242:245] offset:4608
	s_waitcnt vmcnt(2)
	ds_write_b128 v130, v[246:249] offset:5760
	s_waitcnt vmcnt(1)
	ds_write_b128 v130, v[194:197] offset:6912
	s_waitcnt vmcnt(0)
	ds_write_b128 v130, v[198:201] offset:8064
	v_add_f32_e32 v60, v60, v145
	v_mul_f32_e32 v60, 0xbfb8aa3b, v60
	v_exp_f32_e32 v60, v60
	s_waitcnt lgkmcnt(0)
	ds_read_u16 v64, v148
	ds_read_u16 v65, v148 offset:9216
	v_add_f32_e32 v61, v61, v145
	v_add_f32_e32 v60, 1.0, v60
	v_rcp_f32_e32 v60, v60
	s_waitcnt lgkmcnt(1)
	v_lshlrev_b32_e32 v64, 16, v64
	s_waitcnt lgkmcnt(0)
	v_lshlrev_b32_e32 v65, 16, v65
	v_mul_f32_e32 v61, 0xbfb8aa3b, v61
	v_mul_f32_e32 v60, v60, v64
	v_mul_f32_e32 v60, v60, v65
	v_exp_f32_e32 v61, v61
	v_cvt_pk_bf16_f32 v60, v60, s0
	ds_write_b16 v148, v60 offset:9216
	ds_read_u16 v60, v147 offset:144
	v_add_f32_e32 v61, 1.0, v61
	ds_read_u16 v64, v147 offset:9360
	v_rcp_f32_e32 v61, v61
	v_add_f32_e32 v56, v56, v144
	s_waitcnt lgkmcnt(1)
	v_lshlrev_b32_e32 v60, 16, v60
	v_mul_f32_e32 v56, 0xbfb8aa3b, v56
	v_mul_f32_e32 v60, v61, v60
	s_waitcnt lgkmcnt(0)
	v_lshlrev_b32_e32 v61, 16, v64
	v_mul_f32_e32 v60, v60, v61
	v_add_f32_e32 v61, v62, v145
	v_mul_f32_e32 v61, 0xbfb8aa3b, v61
	v_exp_f32_e32 v61, v61
	v_cvt_pk_bf16_f32 v60, v60, s0
	ds_write_b16 v147, v60 offset:9360
	ds_read_u16 v60, v149
	v_add_f32_e32 v61, 1.0, v61
	ds_read_u16 v62, v149 offset:9216
	v_rcp_f32_e32 v61, v61
	v_exp_f32_e32 v56, v56
	s_waitcnt lgkmcnt(1)
	v_lshlrev_b32_e32 v60, 16, v60
	v_add_f32_e32 v57, v57, v144
	v_mul_f32_e32 v60, v61, v60
	s_waitcnt lgkmcnt(0)
	v_lshlrev_b32_e32 v61, 16, v62
	v_mul_f32_e32 v60, v60, v61
	v_add_f32_e32 v61, v63, v145
	v_mul_f32_e32 v61, 0xbfb8aa3b, v61
	v_exp_f32_e32 v61, v61
	v_cvt_pk_bf16_f32 v60, v60, s0
	ds_write_b16 v149, v60 offset:9216
	ds_read_u16 v60, v151
	v_add_f32_e32 v61, 1.0, v61
	v_rcp_f32_e32 v61, v61
	ds_read_u16 v62, v151 offset:9216
	ds_read_u16 v63, v152 offset:32
	ds_read_u16 v64, v152 offset:9248
	v_add_f32_e32 v56, 1.0, v56
	s_waitcnt lgkmcnt(3)
	v_lshlrev_b32_e32 v60, 16, v60
	v_mul_f32_e32 v60, v61, v60
	s_waitcnt lgkmcnt(2)
	v_lshlrev_b32_e32 v61, 16, v62
	v_rcp_f32_e32 v56, v56
	v_mul_f32_e32 v60, v60, v61
	v_cvt_pk_bf16_f32 v60, v60, s0
	ds_write_b16 v151, v60 offset:9216
	s_waitcnt lgkmcnt(2)
	v_lshlrev_b32_e32 v60, 16, v63
	v_mul_f32_e32 v56, v56, v60
	s_waitcnt lgkmcnt(1)
	v_lshlrev_b32_e32 v60, 16, v64
	v_mul_f32_e32 v57, 0xbfb8aa3b, v57
	v_mul_f32_e32 v56, v56, v60
	v_exp_f32_e32 v57, v57
	v_cvt_pk_bf16_f32 v56, v56, s0
	ds_write_b16 v152, v56 offset:9248
	ds_read_u16 v56, v147 offset:176
	v_add_f32_e32 v57, 1.0, v57
	ds_read_u16 v60, v147 offset:9392
	v_rcp_f32_e32 v57, v57
	v_add_f32_e32 v58, v58, v144
	v_mul_f32_e32 v58, 0xbfb8aa3b, v58
	s_waitcnt lgkmcnt(1)
	v_lshlrev_b32_e32 v56, 16, v56
	v_exp_f32_e32 v58, v58
	v_mul_f32_e32 v56, v57, v56
	s_waitcnt lgkmcnt(0)
	v_lshlrev_b32_e32 v57, 16, v60
	v_mul_f32_e32 v56, v56, v57
	v_cvt_pk_bf16_f32 v56, v56, s0
	ds_write_b16 v147, v56 offset:9392
	v_add_f32_e32 v56, 1.0, v58
	v_rcp_f32_e32 v56, v56
	ds_read_u16 v57, v150 offset:32
	ds_read_u16 v58, v150 offset:9248
	ds_read_u16 v60, v151 offset:32
	ds_read_u16 v61, v151 offset:9248
	ds_read_u16 v62, v152 offset:64
	ds_read_u16 v63, v152 offset:9280
	s_waitcnt lgkmcnt(5)
	v_lshlrev_b32_e32 v57, 16, v57
	v_add_f32_e32 v52, v52, v143
	v_mul_f32_e32 v56, v56, v57
	s_waitcnt lgkmcnt(4)
	v_lshlrev_b32_e32 v57, 16, v58
	v_mul_f32_e32 v56, v56, v57
	v_add_f32_e32 v57, v59, v144
	v_mul_f32_e32 v57, 0xbfb8aa3b, v57
	v_exp_f32_e32 v57, v57
	v_mul_f32_e32 v52, 0xbfb8aa3b, v52
	v_exp_f32_e32 v52, v52
	v_cvt_pk_bf16_f32 v56, v56, s0
	v_add_f32_e32 v57, 1.0, v57
	v_rcp_f32_e32 v57, v57
	ds_write_b16 v150, v56 offset:9248
	s_waitcnt lgkmcnt(4)
	v_lshlrev_b32_e32 v56, 16, v60
	v_add_f32_e32 v52, 1.0, v52
	v_mul_f32_e32 v56, v57, v56
	s_waitcnt lgkmcnt(3)
	v_lshlrev_b32_e32 v57, 16, v61
	v_rcp_f32_e32 v52, v52
	v_mul_f32_e32 v56, v56, v57
	v_cvt_pk_bf16_f32 v56, v56, s0
	ds_write_b16 v151, v56 offset:9248
	s_waitcnt lgkmcnt(3)
	v_lshlrev_b32_e32 v56, 16, v62
	v_add_f32_e32 v53, v53, v143
	v_mul_f32_e32 v52, v52, v56
	s_waitcnt lgkmcnt(2)
	v_lshlrev_b32_e32 v56, 16, v63
	v_mul_f32_e32 v53, 0xbfb8aa3b, v53
	v_mul_f32_e32 v52, v52, v56
	v_exp_f32_e32 v53, v53
	v_cvt_pk_bf16_f32 v52, v52, s0
	ds_write_b16 v152, v52 offset:9280
	ds_read_u16 v52, v147 offset:208
	v_add_f32_e32 v53, 1.0, v53
	ds_read_u16 v56, v147 offset:9424
	v_rcp_f32_e32 v53, v53
	v_add_f32_e32 v54, v54, v143
	v_mul_f32_e32 v54, 0xbfb8aa3b, v54
	s_waitcnt lgkmcnt(1)
	v_lshlrev_b32_e32 v52, 16, v52
	v_exp_f32_e32 v54, v54
	v_mul_f32_e32 v52, v53, v52
	s_waitcnt lgkmcnt(0)
	v_lshlrev_b32_e32 v53, 16, v56
	v_mul_f32_e32 v52, v52, v53
	v_cvt_pk_bf16_f32 v52, v52, s0
	ds_write_b16 v147, v52 offset:9424
	v_add_f32_e32 v52, 1.0, v54
	v_rcp_f32_e32 v52, v52
	ds_read_u16 v53, v150 offset:64
	ds_read_u16 v54, v150 offset:9280
	ds_read_u16 v56, v151 offset:64
	ds_read_u16 v57, v151 offset:9280
	ds_read_u16 v58, v152 offset:96
	ds_read_u16 v59, v152 offset:9312
	s_waitcnt lgkmcnt(5)
	v_lshlrev_b32_e32 v53, 16, v53
	v_add_f32_e32 v48, v48, v142
	v_mul_f32_e32 v52, v52, v53
	s_waitcnt lgkmcnt(4)
	v_lshlrev_b32_e32 v53, 16, v54
	v_mul_f32_e32 v52, v52, v53
	v_add_f32_e32 v53, v55, v143
	v_mul_f32_e32 v53, 0xbfb8aa3b, v53
	v_exp_f32_e32 v53, v53
	v_mul_f32_e32 v48, 0xbfb8aa3b, v48
	v_exp_f32_e32 v48, v48
	v_cvt_pk_bf16_f32 v52, v52, s0
	v_add_f32_e32 v53, 1.0, v53
	v_rcp_f32_e32 v53, v53
	ds_write_b16 v150, v52 offset:9280
	s_waitcnt lgkmcnt(4)
	v_lshlrev_b32_e32 v52, 16, v56
	v_add_f32_e32 v48, 1.0, v48
	v_mul_f32_e32 v52, v53, v52
	s_waitcnt lgkmcnt(3)
	v_lshlrev_b32_e32 v53, 16, v57
	v_rcp_f32_e32 v48, v48
	v_mul_f32_e32 v52, v52, v53
	v_cvt_pk_bf16_f32 v52, v52, s0
	ds_write_b16 v151, v52 offset:9280
	s_waitcnt lgkmcnt(3)
	v_lshlrev_b32_e32 v52, 16, v58
	v_add_f32_e32 v49, v49, v142
	v_mul_f32_e32 v48, v48, v52
	s_waitcnt lgkmcnt(2)
	v_lshlrev_b32_e32 v52, 16, v59
	v_mul_f32_e32 v49, 0xbfb8aa3b, v49
	v_mul_f32_e32 v48, v48, v52
	v_exp_f32_e32 v49, v49
	v_cvt_pk_bf16_f32 v48, v48, s0
	ds_write_b16 v152, v48 offset:9312
	ds_read_u16 v48, v147 offset:240
	v_add_f32_e32 v49, 1.0, v49
	ds_read_u16 v52, v147 offset:9456
	v_rcp_f32_e32 v49, v49
	v_add_f32_e32 v51, v51, v142
	s_waitcnt lgkmcnt(1)
	v_lshlrev_b32_e32 v48, 16, v48
	v_mul_f32_e32 v51, 0xbfb8aa3b, v51
	v_mul_f32_e32 v48, v49, v48
	s_waitcnt lgkmcnt(0)
	v_lshlrev_b32_e32 v49, 16, v52
	v_mul_f32_e32 v48, v48, v49
	v_add_f32_e32 v49, v50, v142
	v_mul_f32_e32 v49, 0xbfb8aa3b, v49
	v_exp_f32_e32 v49, v49
	v_cvt_pk_bf16_f32 v48, v48, s0
	ds_write_b16 v147, v48 offset:9456
	ds_read_u16 v48, v150 offset:96
	v_add_f32_e32 v49, 1.0, v49
	v_rcp_f32_e32 v49, v49
	ds_read_u16 v50, v150 offset:9312
	ds_read_u16 v52, v151 offset:96
	ds_read_u16 v53, v151 offset:9312
	v_exp_f32_e32 v51, v51
	s_waitcnt lgkmcnt(3)
	v_lshlrev_b32_e32 v48, 16, v48
	v_mul_f32_e32 v48, v49, v48
	s_waitcnt lgkmcnt(2)
	v_lshlrev_b32_e32 v49, 16, v50
	v_mul_f32_e32 v48, v48, v49
	v_add_f32_e32 v49, 1.0, v51
	v_rcp_f32_e32 v49, v49
	v_cvt_pk_bf16_f32 v48, v48, s0
	ds_write_b16 v150, v48 offset:9312
	s_waitcnt lgkmcnt(2)
	v_lshlrev_b32_e32 v48, 16, v52
	v_add_f32_e32 v44, v44, v145
	v_mul_f32_e32 v48, v49, v48
	s_waitcnt lgkmcnt(1)
	v_lshlrev_b32_e32 v49, 16, v53
	v_mul_f32_e32 v44, 0xbfb8aa3b, v44
	v_mul_f32_e32 v48, v48, v49
	v_exp_f32_e32 v44, v44
	v_cvt_pk_bf16_f32 v48, v48, s0
	ds_write_b16 v151, v48 offset:9312
	ds_read_u16 v48, v153
	v_add_f32_e32 v44, 1.0, v44
	ds_read_u16 v49, v153 offset:9216
	v_rcp_f32_e32 v44, v44
	v_add_f32_e32 v45, v45, v145
	s_waitcnt lgkmcnt(1)
	v_lshlrev_b32_e32 v48, 16, v48
	v_mul_f32_e32 v45, 0xbfb8aa3b, v45
	v_mul_f32_e32 v44, v44, v48
	s_waitcnt lgkmcnt(0)
	v_lshlrev_b32_e32 v48, 16, v49
	v_mul_f32_e32 v44, v44, v48
	v_exp_f32_e32 v45, v45
	v_cvt_pk_bf16_f32 v44, v44, s0
	ds_write_b16 v153, v44 offset:9216
	ds_read_u16 v44, v155
	v_add_f32_e32 v45, 1.0, v45
	ds_read_u16 v48, v155 offset:9216
	v_rcp_f32_e32 v45, v45
	v_add_f32_e32 v40, v40, v144
	s_waitcnt lgkmcnt(1)
	v_lshlrev_b32_e32 v44, 16, v44
	v_mul_f32_e32 v40, 0xbfb8aa3b, v40
	v_mul_f32_e32 v44, v45, v44
	s_waitcnt lgkmcnt(0)
	v_lshlrev_b32_e32 v45, 16, v48
	v_mul_f32_e32 v44, v44, v45
	v_add_f32_e32 v45, v46, v145
	v_mul_f32_e32 v45, 0xbfb8aa3b, v45
	v_exp_f32_e32 v45, v45
	v_cvt_pk_bf16_f32 v44, v44, s0
	ds_write_b16 v155, v44 offset:9216
	ds_read_u16 v44, v156
	v_add_f32_e32 v45, 1.0, v45
	ds_read_u16 v46, v156 offset:9216
	v_rcp_f32_e32 v45, v45
	v_exp_f32_e32 v40, v40
	s_waitcnt lgkmcnt(1)
	v_lshlrev_b32_e32 v44, 16, v44
	v_add_f32_e32 v42, v42, v144
	v_mul_f32_e32 v44, v45, v44
	s_waitcnt lgkmcnt(0)
	v_lshlrev_b32_e32 v45, 16, v46
	v_mul_f32_e32 v44, v44, v45
	v_add_f32_e32 v45, v47, v145
	v_mul_f32_e32 v45, 0xbfb8aa3b, v45
	v_exp_f32_e32 v45, v45
	v_cvt_pk_bf16_f32 v44, v44, s0
	ds_write_b16 v156, v44 offset:9216
	ds_read_u16 v44, v158
	v_add_f32_e32 v45, 1.0, v45
	v_rcp_f32_e32 v45, v45
	ds_read_u16 v46, v158 offset:32
	ds_read_u16 v47, v155 offset:9312
	v_add_f32_e32 v40, 1.0, v40
	s_waitcnt lgkmcnt(2)
	v_lshlrev_b32_e32 v44, 16, v44
	v_mul_f32_e32 v44, v45, v44
	ds_read_u16 v45, v158 offset:9216
	ds_read_u16 v48, v154 offset:32
	ds_read_u16 v49, v154 offset:64
	ds_read_u16 v50, v158 offset:9248
	ds_read_u16 v51, v158 offset:64
	ds_read_u16 v52, v158 offset:9280
	ds_read_u16 v53, v158 offset:9312
	ds_read_u16 v54, v158 offset:96
	s_waitcnt lgkmcnt(7)
	v_lshlrev_b32_e32 v45, 16, v45
	v_rcp_f32_e32 v40, v40
	v_mul_f32_e32 v44, v44, v45
	v_cvt_pk_bf16_f32 v44, v44, s0
	ds_write_b16 v158, v44 offset:9216
	s_waitcnt lgkmcnt(7)
	v_lshlrev_b32_e32 v44, 16, v48
	v_mul_f32_e32 v40, v40, v44
	ds_read_u16 v44, v154 offset:9248
	ds_read_u16 v45, v157 offset:32
	ds_read_u16 v48, v157 offset:9248
	ds_read_u16 v55, v154 offset:9280
	ds_read_u16 v56, v157 offset:64
	ds_read_u16 v57, v157 offset:96
	ds_read_u16 v58, v154 offset:9312
	ds_read_u16 v59, v154 offset:96
	s_waitcnt lgkmcnt(7)
	v_lshlrev_b32_e32 v44, 16, v44
	v_mul_f32_e32 v40, v40, v44
	v_cvt_pk_bf16_f32 v40, v40, s0
	ds_write_b16 v154, v40 offset:9248
	v_add_f32_e32 v40, v41, v144
	v_mul_f32_e32 v40, 0xbfb8aa3b, v40
	v_exp_f32_e32 v40, v40
	v_mul_f32_e32 v42, 0xbfb8aa3b, v42
	v_exp_f32_e32 v42, v42
	ds_read_u16 v41, v155 offset:32
	ds_read_u16 v44, v155 offset:9248
	ds_read_u16 v60, v155 offset:9280
	ds_read_u16 v61, v155 offset:64
	ds_read_u16 v62, v155 offset:96
	v_add_f32_e32 v40, 1.0, v40
	v_rcp_f32_e32 v40, v40
	s_waitcnt lgkmcnt(4)
	v_lshlrev_b32_e32 v41, 16, v41
	v_add_f32_e32 v36, v36, v143
	v_mul_f32_e32 v36, 0xbfb8aa3b, v36
	v_mul_f32_e32 v40, v40, v41
	s_waitcnt lgkmcnt(3)
	v_lshlrev_b32_e32 v41, 16, v44
	v_mul_f32_e32 v40, v40, v41
	v_add_f32_e32 v41, 1.0, v42
	v_rcp_f32_e32 v41, v41
	v_cvt_pk_bf16_f32 v40, v40, s0
	ds_write_b16 v155, v40 offset:9248
	v_lshlrev_b32_e32 v40, 16, v45
	v_mul_f32_e32 v40, v41, v40
	v_lshlrev_b32_e32 v41, 16, v48
	v_mul_f32_e32 v40, v40, v41
	v_add_f32_e32 v41, v43, v144
	v_mul_f32_e32 v41, 0xbfb8aa3b, v41
	v_exp_f32_e32 v41, v41
	v_exp_f32_e32 v36, v36
	v_add_f32_e32 v37, v37, v143
	v_cvt_pk_bf16_f32 v40, v40, s0
	v_add_f32_e32 v41, 1.0, v41
	v_rcp_f32_e32 v41, v41
	v_mul_f32_e32 v37, 0xbfb8aa3b, v37
	ds_write_b16 v157, v40 offset:9248
	v_lshlrev_b32_e32 v40, 16, v46
	v_add_f32_e32 v36, 1.0, v36
	v_exp_f32_e32 v37, v37
	v_mul_f32_e32 v40, v41, v40
	v_lshlrev_b32_e32 v41, 16, v50
	v_rcp_f32_e32 v36, v36
	v_mul_f32_e32 v40, v40, v41
	v_cvt_pk_bf16_f32 v40, v40, s0
	ds_write_b16 v158, v40 offset:9248
	v_lshlrev_b32_e32 v40, 16, v49
	v_add_f32_e32 v37, 1.0, v37
	v_add_f32_e32 v38, v38, v143
	v_mul_f32_e32 v36, v36, v40
	v_lshlrev_b32_e32 v40, 16, v55
	v_rcp_f32_e32 v37, v37
	v_mul_f32_e32 v38, 0xbfb8aa3b, v38
	v_mul_f32_e32 v36, v36, v40
	v_exp_f32_e32 v38, v38
	v_cvt_pk_bf16_f32 v36, v36, s0
	ds_write_b16 v154, v36 offset:9280
	s_waitcnt lgkmcnt(5)
	v_lshlrev_b32_e32 v36, 16, v61
	v_mul_f32_e32 v36, v37, v36
	v_lshlrev_b32_e32 v37, 16, v60
	v_mul_f32_e32 v36, v36, v37
	v_add_f32_e32 v37, 1.0, v38
	v_rcp_f32_e32 v37, v37
	v_cvt_pk_bf16_f32 v36, v36, s0
	ds_write_b16 v155, v36 offset:9280
	v_lshlrev_b32_e32 v36, 16, v56
	v_mul_f32_e32 v36, v37, v36
	ds_read_u16 v37, v157 offset:9280
	v_add_f32_e32 v38, v39, v143
	v_mul_f32_e32 v38, 0xbfb8aa3b, v38
	v_exp_f32_e32 v38, v38
	v_add_f32_e32 v32, v32, v142
	s_waitcnt lgkmcnt(0)
	v_lshlrev_b32_e32 v37, 16, v37
	v_mul_f32_e32 v32, 0xbfb8aa3b, v32
	v_mul_f32_e32 v36, v36, v37
	v_add_f32_e32 v37, 1.0, v38
	v_exp_f32_e32 v32, v32
	v_rcp_f32_e32 v37, v37
	v_add_f32_e32 v33, v33, v142
	v_cvt_pk_bf16_f32 v36, v36, s0
	v_mul_f32_e32 v33, 0xbfb8aa3b, v33
	ds_write_b16 v157, v36 offset:9280
	v_lshlrev_b32_e32 v36, 16, v51
	v_add_f32_e32 v32, 1.0, v32
	v_exp_f32_e32 v33, v33
	v_mul_f32_e32 v36, v37, v36
	v_lshlrev_b32_e32 v37, 16, v52
	v_rcp_f32_e32 v32, v32
	v_mul_f32_e32 v36, v36, v37
	v_cvt_pk_bf16_f32 v36, v36, s0
	ds_write_b16 v158, v36 offset:9280
	v_lshlrev_b32_e32 v36, 16, v59
	v_add_f32_e32 v33, 1.0, v33
	v_mul_f32_e32 v32, v32, v36
	v_lshlrev_b32_e32 v36, 16, v58
	v_rcp_f32_e32 v33, v33
	v_mul_f32_e32 v32, v32, v36
	v_cvt_pk_bf16_f32 v32, v32, s0
	ds_write_b16 v154, v32 offset:9312
	v_lshlrev_b32_e32 v32, 16, v62
	v_mul_f32_e32 v32, v33, v32
	v_lshlrev_b32_e32 v33, 16, v47
	v_mul_f32_e32 v32, v32, v33
	v_add_f32_e32 v33, v34, v142
	v_mul_f32_e32 v33, 0xbfb8aa3b, v33
	v_exp_f32_e32 v33, v33
	ds_read_u16 v39, v157 offset:9312
	v_add_f32_e32 v34, v35, v142
	v_mul_f32_e32 v34, 0xbfb8aa3b, v34
	v_add_f32_e32 v33, 1.0, v33
	v_rcp_f32_e32 v33, v33
	v_exp_f32_e32 v34, v34
	v_cvt_pk_bf16_f32 v32, v32, s0
	ds_write_b16 v155, v32 offset:9312
	v_lshlrev_b32_e32 v32, 16, v57
	v_mul_f32_e32 v32, v33, v32
	s_waitcnt lgkmcnt(1)
	v_lshlrev_b32_e32 v33, 16, v39
	v_mul_f32_e32 v32, v32, v33
	v_add_f32_e32 v33, 1.0, v34
	v_rcp_f32_e32 v33, v33
	v_cvt_pk_bf16_f32 v32, v32, s0
	ds_write_b16 v157, v32 offset:9312
	v_lshlrev_b32_e32 v32, 16, v54
	v_add_f32_e32 v28, v28, v145
	v_mul_f32_e32 v32, v33, v32
	v_lshlrev_b32_e32 v33, 16, v53
	v_mul_f32_e32 v28, 0xbfb8aa3b, v28
	v_mul_f32_e32 v32, v32, v33
	v_exp_f32_e32 v28, v28
	v_cvt_pk_bf16_f32 v32, v32, s0
	ds_write_b16 v158, v32 offset:9312
	ds_read_u16 v32, v159
	v_add_f32_e32 v28, 1.0, v28
	ds_read_u16 v33, v159 offset:9216
	v_rcp_f32_e32 v28, v28
	v_add_f32_e32 v29, v29, v145
	s_waitcnt lgkmcnt(1)
	v_lshlrev_b32_e32 v32, 16, v32
	v_mul_f32_e32 v29, 0xbfb8aa3b, v29
	v_mul_f32_e32 v28, v28, v32
	s_waitcnt lgkmcnt(0)
	v_lshlrev_b32_e32 v32, 16, v33
	v_mul_f32_e32 v28, v28, v32
	v_exp_f32_e32 v29, v29
	v_cvt_pk_bf16_f32 v28, v28, s0
	ds_write_b16 v159, v28 offset:9216
	ds_read_u16 v28, v161
	v_add_f32_e32 v29, 1.0, v29
	ds_read_u16 v32, v161 offset:9216
	v_rcp_f32_e32 v29, v29
	v_add_f32_e32 v24, v24, v144
	s_waitcnt lgkmcnt(1)
	v_lshlrev_b32_e32 v28, 16, v28
	v_mul_f32_e32 v24, 0xbfb8aa3b, v24
	v_mul_f32_e32 v28, v29, v28
	s_waitcnt lgkmcnt(0)
	v_lshlrev_b32_e32 v29, 16, v32
	v_mul_f32_e32 v28, v28, v29
	v_add_f32_e32 v29, v30, v145
	v_mul_f32_e32 v29, 0xbfb8aa3b, v29
	v_exp_f32_e32 v29, v29
	v_cvt_pk_bf16_f32 v28, v28, s0
	ds_write_b16 v161, v28 offset:9216
	ds_read_u16 v28, v162
	v_add_f32_e32 v29, 1.0, v29
	ds_read_u16 v30, v162 offset:9216
	v_rcp_f32_e32 v29, v29
	v_exp_f32_e32 v24, v24
	s_waitcnt lgkmcnt(1)
	v_lshlrev_b32_e32 v28, 16, v28
	v_add_f32_e32 v26, v26, v144
	v_mul_f32_e32 v28, v29, v28
	s_waitcnt lgkmcnt(0)
	v_lshlrev_b32_e32 v29, 16, v30
	v_mul_f32_e32 v28, v28, v29
	v_add_f32_e32 v29, v31, v145
	v_mul_f32_e32 v29, 0xbfb8aa3b, v29
	v_exp_f32_e32 v29, v29
	v_cvt_pk_bf16_f32 v28, v28, s0
	ds_write_b16 v162, v28 offset:9216
	ds_read_u16 v28, v164
	v_add_f32_e32 v29, 1.0, v29
	v_rcp_f32_e32 v29, v29
	ds_read_u16 v30, v164 offset:32
	ds_read_u16 v31, v161 offset:9312
	v_add_f32_e32 v24, 1.0, v24
	s_waitcnt lgkmcnt(2)
	v_lshlrev_b32_e32 v28, 16, v28
	v_mul_f32_e32 v28, v29, v28
	ds_read_u16 v29, v164 offset:9216
	ds_read_u16 v32, v160 offset:32
	ds_read_u16 v33, v160 offset:64
	ds_read_u16 v34, v164 offset:9248
	ds_read_u16 v35, v164 offset:64
	ds_read_u16 v36, v164 offset:9280
	ds_read_u16 v37, v164 offset:9312
	ds_read_u16 v38, v164 offset:96
	s_waitcnt lgkmcnt(7)
	v_lshlrev_b32_e32 v29, 16, v29
	v_rcp_f32_e32 v24, v24
	v_mul_f32_e32 v28, v28, v29
	v_cvt_pk_bf16_f32 v28, v28, s0
	ds_write_b16 v164, v28 offset:9216
	s_waitcnt lgkmcnt(7)
	v_lshlrev_b32_e32 v28, 16, v32
	v_mul_f32_e32 v24, v24, v28
	ds_read_u16 v28, v160 offset:9248
	ds_read_u16 v29, v163 offset:32
	ds_read_u16 v32, v163 offset:9248
	ds_read_u16 v39, v160 offset:9280
	ds_read_u16 v40, v163 offset:64
	ds_read_u16 v41, v163 offset:96
	ds_read_u16 v42, v160 offset:9312
	ds_read_u16 v43, v160 offset:96
	s_waitcnt lgkmcnt(7)
	v_lshlrev_b32_e32 v28, 16, v28
	v_mul_f32_e32 v24, v24, v28
	v_cvt_pk_bf16_f32 v24, v24, s0
	ds_write_b16 v160, v24 offset:9248
	v_add_f32_e32 v24, v25, v144
	v_mul_f32_e32 v24, 0xbfb8aa3b, v24
	v_exp_f32_e32 v24, v24
	v_mul_f32_e32 v26, 0xbfb8aa3b, v26
	v_exp_f32_e32 v26, v26
	ds_read_u16 v25, v161 offset:32
	ds_read_u16 v28, v161 offset:9248
	ds_read_u16 v44, v161 offset:9280
	ds_read_u16 v45, v161 offset:64
	ds_read_u16 v46, v161 offset:96
	v_add_f32_e32 v24, 1.0, v24
	v_rcp_f32_e32 v24, v24
	s_waitcnt lgkmcnt(4)
	v_lshlrev_b32_e32 v25, 16, v25
	v_add_f32_e32 v20, v20, v143
	v_mul_f32_e32 v20, 0xbfb8aa3b, v20
	v_mul_f32_e32 v24, v24, v25
	s_waitcnt lgkmcnt(3)
	v_lshlrev_b32_e32 v25, 16, v28
	v_mul_f32_e32 v24, v24, v25
	v_add_f32_e32 v25, 1.0, v26
	v_rcp_f32_e32 v25, v25
	v_cvt_pk_bf16_f32 v24, v24, s0
	ds_write_b16 v161, v24 offset:9248
	v_lshlrev_b32_e32 v24, 16, v29
	v_mul_f32_e32 v24, v25, v24
	v_lshlrev_b32_e32 v25, 16, v32
	v_mul_f32_e32 v24, v24, v25
	v_add_f32_e32 v25, v27, v144
	v_mul_f32_e32 v25, 0xbfb8aa3b, v25
	v_exp_f32_e32 v25, v25
	v_exp_f32_e32 v20, v20
	v_add_f32_e32 v21, v21, v143
	v_cvt_pk_bf16_f32 v24, v24, s0
	v_add_f32_e32 v25, 1.0, v25
	v_rcp_f32_e32 v25, v25
	v_mul_f32_e32 v21, 0xbfb8aa3b, v21
	ds_write_b16 v163, v24 offset:9248
	v_lshlrev_b32_e32 v24, 16, v30
	v_add_f32_e32 v20, 1.0, v20
	v_exp_f32_e32 v21, v21
	v_mul_f32_e32 v24, v25, v24
	v_lshlrev_b32_e32 v25, 16, v34
	v_rcp_f32_e32 v20, v20
	v_mul_f32_e32 v24, v24, v25
	v_cvt_pk_bf16_f32 v24, v24, s0
	ds_write_b16 v164, v24 offset:9248
	v_lshlrev_b32_e32 v24, 16, v33
	v_add_f32_e32 v21, 1.0, v21
	v_add_f32_e32 v22, v22, v143
	v_mul_f32_e32 v20, v20, v24
	v_lshlrev_b32_e32 v24, 16, v39
	v_rcp_f32_e32 v21, v21
	v_mul_f32_e32 v22, 0xbfb8aa3b, v22
	v_mul_f32_e32 v20, v20, v24
	v_exp_f32_e32 v22, v22
	v_cvt_pk_bf16_f32 v20, v20, s0
	ds_write_b16 v160, v20 offset:9280
	s_waitcnt lgkmcnt(5)
	v_lshlrev_b32_e32 v20, 16, v45
	v_mul_f32_e32 v20, v21, v20
	v_lshlrev_b32_e32 v21, 16, v44
	v_mul_f32_e32 v20, v20, v21
	v_add_f32_e32 v21, 1.0, v22
	v_rcp_f32_e32 v21, v21
	v_cvt_pk_bf16_f32 v20, v20, s0
	ds_write_b16 v161, v20 offset:9280
	v_lshlrev_b32_e32 v20, 16, v40
	v_mul_f32_e32 v20, v21, v20
	ds_read_u16 v21, v163 offset:9280
	v_add_f32_e32 v22, v23, v143
	v_mul_f32_e32 v22, 0xbfb8aa3b, v22
	v_exp_f32_e32 v22, v22
	v_add_f32_e32 v16, v16, v142
	s_waitcnt lgkmcnt(0)
	v_lshlrev_b32_e32 v21, 16, v21
	v_mul_f32_e32 v16, 0xbfb8aa3b, v16
	v_mul_f32_e32 v20, v20, v21
	v_add_f32_e32 v21, 1.0, v22
	v_exp_f32_e32 v16, v16
	v_rcp_f32_e32 v21, v21
	v_add_f32_e32 v17, v17, v142
	v_cvt_pk_bf16_f32 v20, v20, s0
	v_mul_f32_e32 v17, 0xbfb8aa3b, v17
	ds_write_b16 v163, v20 offset:9280
	v_lshlrev_b32_e32 v20, 16, v35
	v_add_f32_e32 v16, 1.0, v16
	v_exp_f32_e32 v17, v17
	v_mul_f32_e32 v20, v21, v20
	v_lshlrev_b32_e32 v21, 16, v36
	v_rcp_f32_e32 v16, v16
	v_mul_f32_e32 v20, v20, v21
	v_cvt_pk_bf16_f32 v20, v20, s0
	ds_write_b16 v164, v20 offset:9280
	v_lshlrev_b32_e32 v20, 16, v43
	v_add_f32_e32 v17, 1.0, v17
	v_mul_f32_e32 v16, v16, v20
	v_lshlrev_b32_e32 v20, 16, v42
	v_rcp_f32_e32 v17, v17
	v_mul_f32_e32 v16, v16, v20
	v_cvt_pk_bf16_f32 v16, v16, s0
	ds_write_b16 v160, v16 offset:9312
	v_lshlrev_b32_e32 v16, 16, v46
	v_mul_f32_e32 v16, v17, v16
	v_lshlrev_b32_e32 v17, 16, v31
	v_mul_f32_e32 v16, v16, v17
	v_add_f32_e32 v17, v18, v142
	v_mul_f32_e32 v17, 0xbfb8aa3b, v17
	v_exp_f32_e32 v17, v17
	ds_read_u16 v23, v163 offset:9312
	v_add_f32_e32 v18, v19, v142
	v_mul_f32_e32 v18, 0xbfb8aa3b, v18
	v_add_f32_e32 v17, 1.0, v17
	v_rcp_f32_e32 v17, v17
	v_exp_f32_e32 v18, v18
	v_cvt_pk_bf16_f32 v16, v16, s0
	ds_write_b16 v161, v16 offset:9312
	v_lshlrev_b32_e32 v16, 16, v41
	v_mul_f32_e32 v16, v17, v16
	s_waitcnt lgkmcnt(1)
	v_lshlrev_b32_e32 v17, 16, v23
	v_mul_f32_e32 v16, v16, v17
	v_add_f32_e32 v17, 1.0, v18
	v_rcp_f32_e32 v17, v17
	v_cvt_pk_bf16_f32 v16, v16, s0
	ds_write_b16 v163, v16 offset:9312
	v_lshlrev_b32_e32 v16, 16, v38
	v_add_f32_e32 v12, v12, v145
	v_mul_f32_e32 v16, v17, v16
	v_lshlrev_b32_e32 v17, 16, v37
	v_mul_f32_e32 v12, 0xbfb8aa3b, v12
	v_mul_f32_e32 v16, v16, v17
	v_exp_f32_e32 v12, v12
	v_cvt_pk_bf16_f32 v16, v16, s0
	ds_write_b16 v164, v16 offset:9312
	ds_read_u16 v16, v165
	v_add_f32_e32 v12, 1.0, v12
	ds_read_u16 v17, v165 offset:9216
	v_rcp_f32_e32 v12, v12
	v_add_f32_e32 v13, v13, v145
	s_waitcnt lgkmcnt(1)
	v_lshlrev_b32_e32 v16, 16, v16
	v_mul_f32_e32 v13, 0xbfb8aa3b, v13
	v_mul_f32_e32 v12, v12, v16
	s_waitcnt lgkmcnt(0)
	v_lshlrev_b32_e32 v16, 16, v17
	v_mul_f32_e32 v12, v12, v16
	v_exp_f32_e32 v13, v13
	v_cvt_pk_bf16_f32 v12, v12, s0
	ds_write_b16 v165, v12 offset:9216
	ds_read_u16 v12, v167
	v_add_f32_e32 v13, 1.0, v13
	ds_read_u16 v16, v167 offset:9216
	v_rcp_f32_e32 v13, v13
	v_add_f32_e32 v0, v0, v144
	s_waitcnt lgkmcnt(1)
	v_lshlrev_b32_e32 v12, 16, v12
	v_mul_f32_e32 v0, 0xbfb8aa3b, v0
	v_mul_f32_e32 v12, v13, v12
	s_waitcnt lgkmcnt(0)
	v_lshlrev_b32_e32 v13, 16, v16
	v_mul_f32_e32 v12, v12, v13
	v_add_f32_e32 v13, v14, v145
	v_mul_f32_e32 v13, 0xbfb8aa3b, v13
	v_exp_f32_e32 v13, v13
	v_cvt_pk_bf16_f32 v12, v12, s0
	ds_write_b16 v167, v12 offset:9216
	ds_read_u16 v12, v168
	v_add_f32_e32 v13, 1.0, v13
	ds_read_u16 v14, v168 offset:9216
	v_rcp_f32_e32 v13, v13
	v_exp_f32_e32 v0, v0
	s_waitcnt lgkmcnt(1)
	v_lshlrev_b32_e32 v12, 16, v12
	v_add_f32_e32 v2, v2, v144
	v_mul_f32_e32 v12, v13, v12
	s_waitcnt lgkmcnt(0)
	v_lshlrev_b32_e32 v13, 16, v14
	v_mul_f32_e32 v12, v12, v13
	v_add_f32_e32 v13, v15, v145
	v_mul_f32_e32 v13, 0xbfb8aa3b, v13
	v_exp_f32_e32 v13, v13
	v_cvt_pk_bf16_f32 v12, v12, s0
	ds_write_b16 v168, v12 offset:9216
	ds_read_u16 v12, v170
	v_add_f32_e32 v13, 1.0, v13
	v_rcp_f32_e32 v13, v13
	ds_read_u16 v14, v170 offset:32
	ds_read_u16 v15, v167 offset:9312
	v_add_f32_e32 v0, 1.0, v0
	s_waitcnt lgkmcnt(2)
	v_lshlrev_b32_e32 v12, 16, v12
	v_mul_f32_e32 v12, v13, v12
	ds_read_u16 v13, v170 offset:9216
	ds_read_u16 v16, v166 offset:32
	ds_read_u16 v17, v166 offset:64
	ds_read_u16 v18, v170 offset:9248
	ds_read_u16 v19, v170 offset:64
	ds_read_u16 v20, v170 offset:9280
	ds_read_u16 v21, v170 offset:9312
	ds_read_u16 v22, v170 offset:96
	s_waitcnt lgkmcnt(7)
	v_lshlrev_b32_e32 v13, 16, v13
	v_rcp_f32_e32 v0, v0
	v_mul_f32_e32 v12, v12, v13
	v_cvt_pk_bf16_f32 v12, v12, s0
	ds_write_b16 v170, v12 offset:9216
	s_waitcnt lgkmcnt(7)
	v_lshlrev_b32_e32 v12, 16, v16
	v_mul_f32_e32 v0, v0, v12
	ds_read_u16 v12, v166 offset:9248
	ds_read_u16 v13, v169 offset:32
	ds_read_u16 v16, v169 offset:9248
	ds_read_u16 v23, v166 offset:9280
	ds_read_u16 v24, v169 offset:64
	ds_read_u16 v25, v169 offset:96
	ds_read_u16 v26, v166 offset:9312
	ds_read_u16 v27, v166 offset:96
	s_waitcnt lgkmcnt(7)
	v_lshlrev_b32_e32 v12, 16, v12
	v_mul_f32_e32 v0, v0, v12
	v_cvt_pk_bf16_f32 v0, v0, s0
	ds_write_b16 v166, v0 offset:9248
	v_add_f32_e32 v0, v1, v144
	v_mul_f32_e32 v0, 0xbfb8aa3b, v0
	v_exp_f32_e32 v0, v0
	v_mul_f32_e32 v2, 0xbfb8aa3b, v2
	v_exp_f32_e32 v2, v2
	ds_read_u16 v1, v167 offset:32
	ds_read_u16 v12, v167 offset:9248
	ds_read_u16 v28, v167 offset:9280
	ds_read_u16 v29, v167 offset:64
	ds_read_u16 v30, v167 offset:96
	v_add_f32_e32 v0, 1.0, v0
	v_rcp_f32_e32 v0, v0
	s_waitcnt lgkmcnt(4)
	v_lshlrev_b32_e32 v1, 16, v1
	s_mov_b64 s[64:65], 0
	v_mul_f32_e32 v0, v0, v1
	s_waitcnt lgkmcnt(3)
	v_lshlrev_b32_e32 v1, 16, v12
	v_mul_f32_e32 v0, v0, v1
	v_add_f32_e32 v1, 1.0, v2
	v_rcp_f32_e32 v1, v1
	v_cvt_pk_bf16_f32 v0, v0, s0
	ds_write_b16 v167, v0 offset:9248
	v_lshlrev_b32_e32 v0, 16, v13
	v_mul_f32_e32 v0, v1, v0
	v_lshlrev_b32_e32 v1, 16, v16
	v_mul_f32_e32 v0, v0, v1
	v_add_f32_e32 v1, v3, v144
	v_mul_f32_e32 v1, 0xbfb8aa3b, v1
	v_exp_f32_e32 v1, v1
	v_add_f32_e32 v2, v8, v143
	v_mul_f32_e32 v2, 0xbfb8aa3b, v2
	v_exp_f32_e32 v2, v2
	v_add_f32_e32 v1, 1.0, v1
	v_rcp_f32_e32 v1, v1
	v_cvt_pk_bf16_f32 v0, v0, s0
	ds_write_b16 v169, v0 offset:9248
	v_lshlrev_b32_e32 v0, 16, v14
	v_mul_f32_e32 v0, v1, v0
	v_lshlrev_b32_e32 v1, 16, v18
	v_mul_f32_e32 v0, v0, v1
	v_add_f32_e32 v1, 1.0, v2
	v_rcp_f32_e32 v1, v1
	v_cvt_pk_bf16_f32 v0, v0, s0
	ds_write_b16 v170, v0 offset:9248
	v_lshlrev_b32_e32 v0, 16, v17
	v_mul_f32_e32 v0, v1, v0
	v_lshlrev_b32_e32 v1, 16, v23
	v_mul_f32_e32 v0, v0, v1
	v_add_f32_e32 v1, v9, v143
	v_mul_f32_e32 v1, 0xbfb8aa3b, v1
	v_exp_f32_e32 v1, v1
	v_add_f32_e32 v2, v10, v143
	v_mul_f32_e32 v2, 0xbfb8aa3b, v2
	v_exp_f32_e32 v2, v2
	v_add_f32_e32 v1, 1.0, v1
	v_rcp_f32_e32 v1, v1
	v_cvt_pk_bf16_f32 v0, v0, s0
	ds_write_b16 v166, v0 offset:9280
	s_waitcnt lgkmcnt(5)
	v_lshlrev_b32_e32 v0, 16, v29
	v_mul_f32_e32 v0, v1, v0
	v_lshlrev_b32_e32 v1, 16, v28
	v_mul_f32_e32 v0, v0, v1
	v_add_f32_e32 v1, 1.0, v2
	v_rcp_f32_e32 v1, v1
	v_cvt_pk_bf16_f32 v0, v0, s0
	ds_write_b16 v167, v0 offset:9280
	v_lshlrev_b32_e32 v0, 16, v24
	v_mul_f32_e32 v0, v1, v0
	ds_read_u16 v1, v169 offset:9280
	v_add_f32_e32 v2, v11, v143
	v_mul_f32_e32 v2, 0xbfb8aa3b, v2
	v_exp_f32_e32 v2, v2
	ds_read_u16 v3, v169 offset:9312
	s_waitcnt lgkmcnt(1)
	v_lshlrev_b32_e32 v1, 16, v1
	v_mul_f32_e32 v0, v0, v1
	v_add_f32_e32 v1, 1.0, v2
	v_rcp_f32_e32 v1, v1
	v_cvt_pk_bf16_f32 v0, v0, s0
	ds_write_b16 v169, v0 offset:9280
	v_lshlrev_b32_e32 v0, 16, v19
	v_mul_f32_e32 v0, v1, v0
	v_lshlrev_b32_e32 v1, 16, v20
	v_mul_f32_e32 v0, v0, v1
	v_add_f32_e32 v1, v4, v142
	v_mul_f32_e32 v1, 0xbfb8aa3b, v1
	v_exp_f32_e32 v1, v1
	v_add_f32_e32 v2, v5, v142
	v_mul_f32_e32 v2, 0xbfb8aa3b, v2
	v_exp_f32_e32 v2, v2
	v_add_f32_e32 v1, 1.0, v1
	v_rcp_f32_e32 v1, v1
	v_cvt_pk_bf16_f32 v0, v0, s0
	ds_write_b16 v170, v0 offset:9280
	v_lshlrev_b32_e32 v0, 16, v27
	v_mul_f32_e32 v0, v1, v0
	v_lshlrev_b32_e32 v1, 16, v26
	v_mul_f32_e32 v0, v0, v1
	v_add_f32_e32 v1, 1.0, v2
	v_rcp_f32_e32 v1, v1
	v_cvt_pk_bf16_f32 v0, v0, s0
	ds_write_b16 v166, v0 offset:9312
	v_lshlrev_b32_e32 v0, 16, v30
	v_mul_f32_e32 v0, v1, v0
	v_lshlrev_b32_e32 v1, 16, v15
	v_mul_f32_e32 v0, v0, v1
	v_add_f32_e32 v1, v6, v142
	v_mul_f32_e32 v1, 0xbfb8aa3b, v1
	v_exp_f32_e32 v1, v1
	v_add_f32_e32 v2, v7, v142
	v_mul_f32_e32 v2, 0xbfb8aa3b, v2
	v_exp_f32_e32 v2, v2
	v_add_f32_e32 v1, 1.0, v1
	v_rcp_f32_e32 v1, v1
	v_cvt_pk_bf16_f32 v0, v0, s0
	ds_write_b16 v167, v0 offset:9312
	v_lshlrev_b32_e32 v0, 16, v25
	v_mul_f32_e32 v0, v1, v0
	s_waitcnt lgkmcnt(4)
	v_lshlrev_b32_e32 v1, 16, v3
	v_mul_f32_e32 v0, v0, v1
	v_add_f32_e32 v1, 1.0, v2
	v_rcp_f32_e32 v1, v1
	v_cvt_pk_bf16_f32 v0, v0, s0
	ds_write_b16 v169, v0 offset:9312
	v_lshlrev_b32_e32 v0, 16, v22
	v_mul_f32_e32 v0, v1, v0
	v_lshlrev_b32_e32 v1, 16, v21
	v_mul_f32_e32 v0, v0, v1
	v_cvt_pk_bf16_f32 v0, v0, s0
	ds_write_b16 v170, v0 offset:9312
	s_waitcnt lgkmcnt(0)
	v_mov_b32_e32 v0, v130
